# S3 scan-apply chunk body hand-written: all chunk loads batched up front (gate quad as dwordx2 + u + gate), fwd/bwd recurrences from registers, no LDS, 4-step interleaved coefficient chains; same f32 m
# speedup vs baseline: 1.0321x; 1.0296x over previous
; __device__ __forceinline__ float fast_sigmoid(float x) { return __builtin_amdgcn_rcpf(1.f + __builtin_amdgcn_exp2f(-1.4426950408889634f * x)); }
; __device__ __forceinline__ float bf2f(unsigned short h) { return __uint_as_float(((unsigned)h) << 16); }
; __device__ __forceinline__ float bflo(unsigned w) { return __uint_as_float(w << 16); }
; __device__ __forceinline__ float bfhi(unsigned w) { return __uint_as_float(w & 0xffff0000u); }
; __device__ __forceinline__ void scan_coef(float r, float i, float u, float sp8, float& a, float& b) { const float la = -sp8 * r; a = __expf(la); b = __builtin_amdgcn_sqrtf(fmaxf((1.f - a) * (1.f + a), 0.f)) * (i * u); }
; __global__ void __launch_bounds__(512) mega_fwd(Params P) {
;     ...
;             for (int c = bx; c < NCHUNK; c += G) {
;     ...
;                 const int ch = tid, m0 = c * 32; const float spf = 8.f * log1pf(__expf(-lam[ch])), spb = 8.f * log1pf(__expf(-lam[512 + ch]));
;                 const float brf = b_rgr[ch], bif = b_rgi[ch], brb = b_rgr[512 + ch], bib = b_rgi[512 + ch];
;     ...
;                 float hf = 0.f, hb = 0.f;
;     ...
;                 float hf = SCAR[((size_t)c * 512 + ch) * 2], hb = SCAR[((size_t)c * 512 + ch) * 2 + 1];
;     ...
; #pragma unroll 4
;                 for (int t = 0; t < 32; ++t) { const bf16_t* gp = XN + (size_t)(m0 + t) * 2048; const float u = bf2f(UC[(size_t)(m0 + t) * 512 + ch]);
;                     const unsigned g2 = *(const unsigned*)(gp + ch * 4);
;                     float a, b; scan_coef(pg8::fast_sigmoid(bflo(g2) + brf), pg8::fast_sigmoid(bfhi(g2) + bif), u, spf, a, b); hf = a * hf + b; hl[t * 512 + ch] = hf; }
;                 for (int tb = 28; tb >= 0; tb -= 4) { float rr[4], ii[4], uu[4], gg[4];
; #pragma unroll
;                     for (int k = 0; k < 4; ++k) { const bf16_t* gp = XN + (size_t)(m0 + tb + k) * 2048; { const unsigned g2 = *(const unsigned*)(gp + ch * 4 + 2); rr[k] = bflo(g2); ii[k] = bfhi(g2); }
;                         uu[k] = bf2f(UC[(size_t)(m0 + tb + k) * 512 + ch]); gg[k] = bf2f(GT[(size_t)(m0 + tb + k) * 512 + ch]); }
.LBB0_1327:
	global_load_dword v16, v[0:1], off
	s_mov_b32 s38, 0x3f2aaaab
	s_ashr_i32 s55, s54, 31
	s_mov_b32 s47, 0
	s_waitcnt vmcnt(0)
	v_lshlrev_b32_e32 v192, 2, v8
	s_lshl_b32 s40, s29, 12
	s_add_u32 s48, s44, s40
	s_addc_u32 s49, s45, 0
	s_add_u32 s48, s48, 0x8b00000
	s_addc_u32 s49, s49, 0
	s_lshl_b32 s40, s29, 10
	s_add_u32 s50, s44, s40
	s_addc_u32 s51, s45, 0
	s_add_u32 s50, s50, 0x2d400000
	s_addc_u32 s51, s51, 0
	s_lshl_b32 s40, s29, 10
	s_add_u32 s52, s44, s40
	s_addc_u32 s53, s45, 0
	s_add_u32 s52, s52, 0x25700000
	s_addc_u32 s53, s53, 0
	global_load_dwordx2 v[64:65], v192, s[48:49]
	global_load_ushort v66, v8, s[50:51]
	global_load_ushort v67, v8, s[52:53]
	s_add_u32 s48, s48, 0x1000
	s_addc_u32 s49, s49, 0
	global_load_dwordx2 v[68:69], v192, s[48:49]
	global_load_ushort v70, v8, s[50:51] offset:1024
	global_load_ushort v71, v8, s[52:53] offset:1024
	s_add_u32 s48, s48, 0x1000
	s_addc_u32 s49, s49, 0
	global_load_dwordx2 v[72:73], v192, s[48:49]
	global_load_ushort v74, v8, s[50:51] offset:2048
	global_load_ushort v75, v8, s[52:53] offset:2048
	s_add_u32 s48, s48, 0x1000
	s_addc_u32 s49, s49, 0
	global_load_dwordx2 v[76:77], v192, s[48:49]
	global_load_ushort v78, v8, s[50:51] offset:3072
	global_load_ushort v79, v8, s[52:53] offset:3072
	s_add_u32 s48, s48, 0x1000
	s_addc_u32 s49, s49, 0
	s_add_u32 s50, s50, 0x1000
	s_addc_u32 s51, s51, 0
	s_add_u32 s52, s52, 0x1000
	s_addc_u32 s53, s53, 0
	global_load_dwordx2 v[80:81], v192, s[48:49]
	global_load_ushort v82, v8, s[50:51]
	global_load_ushort v83, v8, s[52:53]
	s_add_u32 s48, s48, 0x1000
	s_addc_u32 s49, s49, 0
	global_load_dwordx2 v[84:85], v192, s[48:49]
	global_load_ushort v86, v8, s[50:51] offset:1024
	global_load_ushort v87, v8, s[52:53] offset:1024
	s_add_u32 s48, s48, 0x1000
	s_addc_u32 s49, s49, 0
	global_load_dwordx2 v[88:89], v192, s[48:49]
	global_load_ushort v90, v8, s[50:51] offset:2048
	global_load_ushort v91, v8, s[52:53] offset:2048
	s_add_u32 s48, s48, 0x1000
	s_addc_u32 s49, s49, 0
	global_load_dwordx2 v[92:93], v192, s[48:49]
	global_load_ushort v94, v8, s[50:51] offset:3072
	global_load_ushort v95, v8, s[52:53] offset:3072
	s_add_u32 s48, s48, 0x1000
	s_addc_u32 s49, s49, 0
	s_add_u32 s50, s50, 0x1000
	s_addc_u32 s51, s51, 0
	s_add_u32 s52, s52, 0x1000
	s_addc_u32 s53, s53, 0
	global_load_dwordx2 v[96:97], v192, s[48:49]
	global_load_ushort v98, v8, s[50:51]
	global_load_ushort v99, v8, s[52:53]
	s_add_u32 s48, s48, 0x1000
	s_addc_u32 s49, s49, 0
	global_load_dwordx2 v[100:101], v192, s[48:49]
	global_load_ushort v102, v8, s[50:51] offset:1024
	global_load_ushort v103, v8, s[52:53] offset:1024
	s_add_u32 s48, s48, 0x1000
	s_addc_u32 s49, s49, 0
	global_load_dwordx2 v[104:105], v192, s[48:49]
	global_load_ushort v106, v8, s[50:51] offset:2048
	global_load_ushort v107, v8, s[52:53] offset:2048
	s_add_u32 s48, s48, 0x1000
	s_addc_u32 s49, s49, 0
	global_load_dwordx2 v[108:109], v192, s[48:49]
	global_load_ushort v110, v8, s[50:51] offset:3072
	global_load_ushort v111, v8, s[52:53] offset:3072
	s_add_u32 s48, s48, 0x1000
	s_addc_u32 s49, s49, 0
	s_add_u32 s50, s50, 0x1000
	s_addc_u32 s51, s51, 0
	s_add_u32 s52, s52, 0x1000
	s_addc_u32 s53, s53, 0
	global_load_dwordx2 v[112:113], v192, s[48:49]
	global_load_ushort v114, v8, s[50:51]
	global_load_ushort v115, v8, s[52:53]
	s_add_u32 s48, s48, 0x1000
	s_addc_u32 s49, s49, 0
	global_load_dwordx2 v[116:117], v192, s[48:49]
	global_load_ushort v118, v8, s[50:51] offset:1024
	global_load_ushort v119, v8, s[52:53] offset:1024
	s_add_u32 s48, s48, 0x1000
	s_addc_u32 s49, s49, 0
	global_load_dwordx2 v[120:121], v192, s[48:49]
	global_load_ushort v122, v8, s[50:51] offset:2048
	global_load_ushort v123, v8, s[52:53] offset:2048
	s_add_u32 s48, s48, 0x1000
	s_addc_u32 s49, s49, 0
	global_load_dwordx2 v[124:125], v192, s[48:49]
	global_load_ushort v126, v8, s[50:51] offset:3072
	global_load_ushort v127, v8, s[52:53] offset:3072
	s_add_u32 s48, s48, 0x1000
	s_addc_u32 s49, s49, 0
	s_add_u32 s50, s50, 0x1000
	s_addc_u32 s51, s51, 0
	s_add_u32 s52, s52, 0x1000
	s_addc_u32 s53, s53, 0
	v_mul_f32_e32 v16, 0xbfb8aa3b, v16
	v_exp_f32_e32 v18, v16
	s_nop 0
	v_add_f32_e32 v19, 1.0, v18
	v_add_f32_e32 v16, -1.0, v19
	v_sub_f32_e32 v17, v16, v19
	v_add_f32_e32 v17, 1.0, v17
	v_sub_f32_e32 v16, v18, v16
	v_add_f32_e32 v20, v16, v17
	v_frexp_mant_f32_e32 v16, v19
	v_cmp_gt_f32_e32 vcc, s38, v16
	v_cvt_f64_f32_e32 v[16:17], v19
	v_frexp_exp_i32_f64_e32 v16, v[16:17]
	v_subbrev_co_u32_e32 v16, vcc, 0, v16, vcc
	v_sub_u32_e32 v17, 0, v16
	v_ldexp_f32 v19, v19, v17
	v_ldexp_f32 v17, v20, v17
	v_add_f32_e32 v20, -1.0, v19
	v_add_f32_e32 v21, 1.0, v20
	v_sub_f32_e32 v21, v19, v21
	v_add_f32_e32 v21, v17, v21
	v_add_f32_e32 v22, v20, v21
	v_sub_f32_e32 v20, v22, v20
	v_sub_f32_e32 v20, v21, v20
	v_add_f32_e32 v21, 1.0, v19
	v_add_f32_e32 v23, -1.0, v21
	v_sub_f32_e32 v19, v19, v23
	v_add_f32_e32 v17, v17, v19
	v_add_f32_e32 v19, v21, v17
	v_sub_f32_e32 v21, v19, v21
	v_sub_f32_e32 v17, v17, v21
	v_rcp_f32_e32 v21, v19
	v_cvt_f32_i32_e32 v16, v16
	s_mov_b32 s38, 0x3f317218
	v_mul_f32_e32 v23, v22, v21
	v_mul_f32_e32 v24, v19, v23
	v_fma_f32 v25, v23, v19, -v24
	v_fmac_f32_e32 v25, v23, v17
	v_add_f32_e32 v26, v24, v25
	v_sub_f32_e32 v27, v22, v26
	v_sub_f32_e32 v22, v22, v27
	v_sub_f32_e32 v24, v26, v24
	v_sub_f32_e32 v22, v22, v26
	v_add_f32_e32 v20, v20, v22
	v_sub_f32_e32 v22, v24, v25
	v_add_f32_e32 v20, v22, v20
	v_add_f32_e32 v22, v27, v20
	v_mul_f32_e32 v24, v21, v22
	v_mul_f32_e32 v25, v19, v24
	v_fma_f32 v19, v24, v19, -v25
	v_fmac_f32_e32 v19, v24, v17
	v_sub_f32_e32 v17, v27, v22
	v_add_f32_e32 v17, v20, v17
	v_add_f32_e32 v20, v25, v19
; __device__ __forceinline__ float fast_sigmoid(float x) { return __builtin_amdgcn_rcpf(1.f + __builtin_amdgcn_exp2f(-1.4426950408889634f * x)); }
; __device__ __forceinline__ float bf2f(unsigned short h) { return __uint_as_float(((unsigned)h) << 16); }
; __device__ __forceinline__ float bflo(unsigned w) { return __uint_as_float(w << 16); }
; __device__ __forceinline__ float bfhi(unsigned w) { return __uint_as_float(w & 0xffff0000u); }
; __device__ __forceinline__ void scan_coef(float r, float i, float u, float sp8, float& a, float& b) { const float la = -sp8 * r; a = __expf(la); b = __builtin_amdgcn_sqrtf(fmaxf((1.f - a) * (1.f + a), 0.f)) * (i * u); }
; __global__ void __launch_bounds__(512) mega_fwd(Params P) {
;     ...
;                 const int ch = tid, m0 = c * 32; const float spf = 8.f * log1pf(__expf(-lam[ch])), spb = 8.f * log1pf(__expf(-lam[512 + ch]));
;                 const float brf = b_rgr[ch], bif = b_rgi[ch], brb = b_rgr[512 + ch], bib = b_rgi[512 + ch];
;     ...
;                 float hf = 0.f, hb = 0.f;
;     ...
;                 float hf = SCAR[((size_t)c * 512 + ch) * 2], hb = SCAR[((size_t)c * 512 + ch) * 2 + 1];
;     ...
; #pragma unroll 4
;                 for (int t = 0; t < 32; ++t) { const bf16_t* gp = XN + (size_t)(m0 + t) * 2048; const float u = bf2f(UC[(size_t)(m0 + t) * 512 + ch]);
;                     const unsigned g2 = *(const unsigned*)(gp + ch * 4);
;                     float a, b; scan_coef(pg8::fast_sigmoid(bflo(g2) + brf), pg8::fast_sigmoid(bfhi(g2) + bif), u, spf, a, b); hf = a * hf + b; hl[t * 512 + ch] = hf; }
	v_sub_f32_e32 v26, v22, v20
	v_sub_f32_e32 v22, v22, v26
	v_sub_f32_e32 v25, v20, v25
	v_sub_f32_e32 v20, v22, v20
	v_add_f32_e32 v17, v17, v20
	v_sub_f32_e32 v19, v25, v19
	v_add_f32_e32 v17, v19, v17
	v_add_f32_e32 v19, v23, v24
	v_add_f32_e32 v17, v26, v17
	v_sub_f32_e32 v20, v19, v23
	v_mul_f32_e32 v17, v21, v17
	v_sub_f32_e32 v20, v24, v20
	v_add_f32_e32 v17, v20, v17
	v_mul_f32_e32 v23, 0x3f317218, v16
	v_add_f32_e32 v20, v19, v17
	v_fma_f32 v24, v16, s38, -v23
	v_mul_f32_e32 v21, v20, v20
	v_mov_b32_e32 v22, 0x3ecc95a3
	v_fmac_f32_e32 v24, 0xb102e308, v16
	v_sub_f32_e32 v16, v20, v19
	v_fmamk_f32 v22, v21, 0x3e9b6dac, v22
	v_sub_f32_e32 v16, v17, v16
	v_add_f32_e32 v17, v23, v24
	v_fmaak_f32 v22, v21, v22, 0x3f2aaada
	v_sub_f32_e32 v19, v17, v23
	v_ldexp_f32 v23, v20, 1
	v_mul_f32_e32 v20, v20, v21
	v_mul_f32_e32 v20, v20, v22
	v_add_f32_e32 v21, v23, v20
	v_sub_f32_e32 v22, v21, v23
	v_ldexp_f32 v16, v16, 1
	v_sub_f32_e32 v20, v20, v22
	v_add_f32_e32 v16, v16, v20
	v_add_f32_e32 v20, v21, v16
	v_sub_f32_e32 v21, v20, v21
	v_sub_f32_e32 v16, v16, v21
	v_add_f32_e32 v21, v17, v20
	v_sub_f32_e32 v22, v21, v17
	v_sub_f32_e32 v23, v21, v22
	v_sub_f32_e32 v19, v24, v19
	v_sub_f32_e32 v17, v17, v23
	v_sub_f32_e32 v20, v20, v22
	v_add_f32_e32 v17, v20, v17
	v_add_f32_e32 v20, v19, v16
	v_sub_f32_e32 v22, v20, v19
	v_sub_f32_e32 v23, v20, v22
	v_sub_f32_e32 v19, v19, v23
	v_sub_f32_e32 v16, v16, v22
	v_add_f32_e32 v17, v20, v17
	v_add_f32_e32 v16, v16, v19
	v_add_f32_e32 v19, v21, v17
	v_sub_f32_e32 v20, v19, v21
	v_sub_f32_e32 v17, v17, v20
	v_add_f32_e32 v16, v16, v17
	s_mov_b32 s38, 0x7f800000
	v_add_f32_e32 v16, v19, v16
	v_cmp_neq_f32_e32 vcc, s38, v18
	s_mov_b32 s38, 0x33800000
	v_mov_b32_e32 v19, v40
	v_cndmask_b32_e32 v16, v208, v16, vcc
	v_cmp_ngt_f32_e32 vcc, -1.0, v18
	s_nop 1
	v_cndmask_b32_e32 v16, v197, v16, vcc
	v_cmp_neq_f32_e32 vcc, -1.0, v18
	s_nop 1
	v_cndmask_b32_e32 v16, v252, v16, vcc
	v_cmp_lt_f32_e64 vcc, |v18|, s38
	s_lshl_b64 s[38:39], s[54:55], 12
	v_lshl_add_u64 v[20:21], v[6:7], 0, s[38:39]
	v_cndmask_b32_e32 v18, v16, v18, vcc
	global_load_dword v28, v[0:1], off offset:2048
	global_load_dword v16, v[2:3], off
	global_load_dword v17, v[4:5], off
	global_load_dword v41, v[2:3], off offset:2048
	global_load_dword v42, v[4:5], off offset:2048
	global_load_dwordx2 v[32:33], v[20:21], off
	v_mul_f32_e32 v18, 0xc1000000, v18
	s_waitcnt vmcnt(0)
	v_mov_b32_e32 v198, v16
	v_mov_b32_e32 v199, v17
	v_mov_b32_e32 v200, v18
	v_mov_b32_e32 v201, v32
	s_ashr_i32 s53, s52, 31
	v_mul_f32_e32 v28, 0xbfb8aa3b, v28
	s_lshl_b64 s[38:39], s[52:53], 10
	v_exp_f32_e32 v32, v28
	v_lshl_add_u64 v[16:17], v[8:9], 0, s[38:39]
	s_lshl_b64 s[38:39], s[52:53], 12
	s_ashr_i32 s51, s50, 31
	v_lshl_add_u64 v[18:19], v[14:15], 0, s[38:39]
	s_lshl_b64 s[38:39], s[50:51], 10
	v_lshl_add_u64 v[20:21], v[8:9], 0, s[38:39]
	s_lshl_b64 s[38:39], s[50:51], 12
	s_ashr_i32 s49, s48, 31
	v_lshl_add_u64 v[22:23], v[14:15], 0, s[38:39]
	s_lshl_b64 s[38:39], s[48:49], 10
	v_add_f32_e32 v36, 1.0, v32
	v_lshl_add_u64 v[24:25], v[8:9], 0, s[38:39]
	s_lshl_b64 s[38:39], s[48:49], 12
	s_ashr_i32 s47, s46, 31
	v_add_f32_e32 v34, -1.0, v36
	v_lshl_add_u64 v[26:27], v[14:15], 0, s[38:39]
	s_lshl_b64 s[38:39], s[46:47], 10
	v_sub_f32_e32 v35, v34, v36
	v_lshl_add_u64 v[28:29], v[8:9], 0, s[38:39]
	s_lshl_b64 s[38:39], s[46:47], 12
	v_add_f32_e32 v35, 1.0, v35
	v_sub_f32_e32 v34, v32, v34
	v_lshl_add_u64 v[30:31], v[14:15], 0, s[38:39]
	v_add_f32_e32 v37, v34, v35
	v_frexp_mant_f32_e32 v38, v36
	v_cvt_f64_f32_e32 v[34:35], v36
	s_mov_b32 s38, 0x3f2aaaab
	v_frexp_exp_i32_f64_e32 v34, v[34:35]
	v_cmp_gt_f32_e32 vcc, s38, v38
	s_mov_b32 s38, 0x3f317218
	s_mov_b32 s47, 0xe000
	v_subbrev_co_u32_e32 v34, vcc, 0, v34, vcc
	v_sub_u32_e32 v35, 0, v34
	v_ldexp_f32 v36, v36, v35
	v_ldexp_f32 v35, v37, v35
	v_add_f32_e32 v37, -1.0, v36
	v_add_f32_e32 v43, 1.0, v36
	v_add_f32_e32 v38, 1.0, v37
	v_add_f32_e32 v44, -1.0, v43
	v_sub_f32_e32 v38, v36, v38
	v_sub_f32_e32 v36, v36, v44
	v_add_f32_e32 v38, v35, v38
	v_add_f32_e32 v35, v35, v36
	v_add_f32_e32 v36, v43, v35
	v_rcp_f32_e32 v44, v36
	v_add_f32_e32 v39, v37, v38
	v_sub_f32_e32 v37, v39, v37
	v_sub_f32_e32 v37, v38, v37
	v_sub_f32_e32 v38, v36, v43
	v_sub_f32_e32 v35, v35, v38
	v_mul_f32_e32 v38, v39, v44
	v_mul_f32_e32 v43, v36, v38
	v_fma_f32 v45, v38, v36, -v43
	v_fmac_f32_e32 v45, v38, v35
	v_add_f32_e32 v46, v43, v45
	v_sub_f32_e32 v47, v39, v46
	v_sub_f32_e32 v39, v39, v47
	v_sub_f32_e32 v43, v46, v43
	v_sub_f32_e32 v39, v39, v46
	v_add_f32_e32 v37, v37, v39
	v_sub_f32_e32 v39, v43, v45
	v_add_f32_e32 v37, v39, v37
	v_add_f32_e32 v39, v47, v37
	v_mul_f32_e32 v43, v44, v39
	v_mul_f32_e32 v45, v36, v43
	v_fma_f32 v36, v43, v36, -v45
	v_fmac_f32_e32 v36, v43, v35
	v_sub_f32_e32 v35, v47, v39
	v_add_f32_e32 v35, v37, v35
	v_add_f32_e32 v37, v45, v36
	v_sub_f32_e32 v46, v39, v37
	v_sub_f32_e32 v39, v39, v46
	v_sub_f32_e32 v45, v37, v45
	v_sub_f32_e32 v37, v39, v37
	v_add_f32_e32 v35, v35, v37
	v_sub_f32_e32 v36, v45, v36
	v_cvt_f32_i32_e32 v34, v34
	v_add_f32_e32 v35, v36, v35
	v_add_f32_e32 v36, v38, v43
	v_add_f32_e32 v35, v46, v35
	v_sub_f32_e32 v37, v36, v38
	v_mul_f32_e32 v35, v44, v35
	v_sub_f32_e32 v37, v43, v37
	v_add_f32_e32 v35, v37, v35
	v_mul_f32_e32 v43, 0x3f317218, v34
	v_add_f32_e32 v37, v36, v35
	v_fma_f32 v44, v34, s38, -v43
	v_mul_f32_e32 v38, v37, v37
	v_mov_b32_e32 v39, 0x3ecc95a3
	v_fmac_f32_e32 v44, 0xb102e308, v34
	v_sub_f32_e32 v34, v37, v36
	v_fmamk_f32 v39, v38, 0x3e9b6dac, v39
	v_sub_f32_e32 v34, v35, v34
	v_add_f32_e32 v35, v43, v44
	v_fmaak_f32 v39, v38, v39, 0x3f2aaada
	v_sub_f32_e32 v36, v35, v43
; __device__ __forceinline__ float fast_sigmoid(float x) { return __builtin_amdgcn_rcpf(1.f + __builtin_amdgcn_exp2f(-1.4426950408889634f * x)); }
; __device__ __forceinline__ float bf2f(unsigned short h) { return __uint_as_float(((unsigned)h) << 16); }
; __device__ __forceinline__ float bflo(unsigned w) { return __uint_as_float(w << 16); }
; __device__ __forceinline__ float bfhi(unsigned w) { return __uint_as_float(w & 0xffff0000u); }
; __device__ __forceinline__ void scan_coef(float r, float i, float u, float sp8, float& a, float& b) { const float la = -sp8 * r; a = __expf(la); b = __builtin_amdgcn_sqrtf(fmaxf((1.f - a) * (1.f + a), 0.f)) * (i * u); }
; __global__ void __launch_bounds__(512) mega_fwd(Params P) {
;     ...
;                 const int ch = tid, m0 = c * 32; const float spf = 8.f * log1pf(__expf(-lam[ch])), spb = 8.f * log1pf(__expf(-lam[512 + ch]));
;     ...
;                 for (int t = 0; t < 32; ++t) { const bf16_t* gp = XN + (size_t)(m0 + t) * 2048; const float u = bf2f(UC[(size_t)(m0 + t) * 512 + ch]);
;                     const unsigned g2 = *(const unsigned*)(gp + ch * 4);
;                     float a, b; scan_coef(pg8::fast_sigmoid(bflo(g2) + brf), pg8::fast_sigmoid(bfhi(g2) + bif), u, spf, a, b); hf = a * hf + b; hl[t * 512 + ch] = hf; }
	v_ldexp_f32 v43, v37, 1
	v_mul_f32_e32 v37, v37, v38
	v_mul_f32_e32 v37, v37, v39
	v_add_f32_e32 v38, v43, v37
	v_sub_f32_e32 v39, v38, v43
	v_ldexp_f32 v34, v34, 1
	v_sub_f32_e32 v37, v37, v39
	v_add_f32_e32 v34, v34, v37
	v_add_f32_e32 v37, v38, v34
	v_sub_f32_e32 v38, v37, v38
	v_sub_f32_e32 v34, v34, v38
	v_add_f32_e32 v38, v35, v37
	v_sub_f32_e32 v39, v38, v35
	v_sub_f32_e32 v43, v38, v39
	v_sub_f32_e32 v36, v44, v36
	v_sub_f32_e32 v35, v35, v43
	v_sub_f32_e32 v37, v37, v39
	v_add_f32_e32 v35, v37, v35
	v_add_f32_e32 v37, v36, v34
	v_sub_f32_e32 v39, v37, v36
	v_sub_f32_e32 v43, v37, v39
	v_sub_f32_e32 v36, v36, v43
	v_sub_f32_e32 v34, v34, v39
	v_add_f32_e32 v35, v37, v35
	v_add_f32_e32 v34, v34, v36
	v_add_f32_e32 v36, v38, v35
	v_sub_f32_e32 v37, v36, v38
	v_sub_f32_e32 v35, v35, v37
	v_add_f32_e32 v34, v34, v35
	s_mov_b32 s38, 0x7f800000
	v_add_f32_e32 v34, v36, v34
	v_cmp_neq_f32_e32 vcc, s38, v32
	s_mov_b32 s38, 0x33800000
	s_nop 0
	v_cndmask_b32_e32 v34, v208, v34, vcc
	v_cmp_ngt_f32_e32 vcc, -1.0, v32
	s_nop 1
	v_cndmask_b32_e32 v34, v197, v34, vcc
	v_cmp_neq_f32_e32 vcc, -1.0, v32
	s_nop 1
	v_cndmask_b32_e32 v34, v252, v34, vcc
	v_cmp_lt_f32_e64 vcc, |v32|, s38
	s_nop 1
	v_cndmask_b32_e32 v32, v34, v32, vcc
	v_mul_f32_e32 v43, 0xc1000000, v32
	v_mov_b32_e32 v32, v33
	s_add_i32 s40, s29, 16
	s_lshl_b32 s40, s40, 12
	s_add_u32 s48, s44, s40
	s_addc_u32 s49, s45, 0
	s_add_u32 s48, s48, 0x8b00000
	s_addc_u32 s49, s49, 0
	s_add_i32 s40, s29, 16
	s_lshl_b32 s40, s40, 10
	s_add_u32 s50, s44, s40
	s_addc_u32 s51, s45, 0
	s_add_u32 s50, s50, 0x2d400000
	s_addc_u32 s51, s51, 0
	s_add_i32 s40, s29, 16
	s_lshl_b32 s40, s40, 10
	s_add_u32 s52, s44, s40
	s_addc_u32 s53, s45, 0
	s_add_u32 s52, s52, 0x25700000
	s_addc_u32 s53, s53, 0
	s_add_i32 s40, s29, 28
	s_lshl_b32 s40, s40, 10
	s_add_u32 s56, s44, s40
	s_addc_u32 s57, s45, 0
	s_add_u32 s56, s56, 0x2fc00000
	s_addc_u32 s57, s57, 0
	global_load_dwordx2 v[128:129], v192, s[48:49]
	global_load_ushort v130, v8, s[50:51]
	global_load_ushort v131, v8, s[52:53]
	s_add_u32 s48, s48, 0x1000
	s_addc_u32 s49, s49, 0
	global_load_dwordx2 v[132:133], v192, s[48:49]
	global_load_ushort v134, v8, s[50:51] offset:1024
	global_load_ushort v135, v8, s[52:53] offset:1024
	s_add_u32 s48, s48, 0x1000
	s_addc_u32 s49, s49, 0
	global_load_dwordx2 v[136:137], v192, s[48:49]
	global_load_ushort v138, v8, s[50:51] offset:2048
	global_load_ushort v139, v8, s[52:53] offset:2048
	s_add_u32 s48, s48, 0x1000
	s_addc_u32 s49, s49, 0
	global_load_dwordx2 v[140:141], v192, s[48:49]
	global_load_ushort v142, v8, s[50:51] offset:3072
	global_load_ushort v143, v8, s[52:53] offset:3072
	s_add_u32 s48, s48, 0x1000
	s_addc_u32 s49, s49, 0
	s_add_u32 s50, s50, 0x1000
	s_addc_u32 s51, s51, 0
	s_add_u32 s52, s52, 0x1000
	s_addc_u32 s53, s53, 0
	v_lshlrev_b32_e32 v48, 16, v64
	v_lshlrev_b32_e32 v51, 16, v68
	v_lshlrev_b32_e32 v54, 16, v72
	v_lshlrev_b32_e32 v57, 16, v76
	v_and_b32_e32 v49, 0xffff0000, v64
	v_and_b32_e32 v52, 0xffff0000, v68
	v_and_b32_e32 v55, 0xffff0000, v72
	v_and_b32_e32 v58, 0xffff0000, v76
	v_add_f32_e32 v48, v198, v48
	v_add_f32_e32 v51, v198, v51
	v_add_f32_e32 v54, v198, v54
	v_add_f32_e32 v57, v198, v57
	v_add_f32_e32 v49, v199, v49
	v_add_f32_e32 v52, v199, v52
	v_add_f32_e32 v55, v199, v55
	v_add_f32_e32 v58, v199, v58
	v_mul_f32_e32 v48, 0xbfb8aa3b, v48
	v_mul_f32_e32 v51, 0xbfb8aa3b, v51
	v_mul_f32_e32 v54, 0xbfb8aa3b, v54
	v_mul_f32_e32 v57, 0xbfb8aa3b, v57
	v_mul_f32_e32 v49, 0xbfb8aa3b, v49
	v_mul_f32_e32 v52, 0xbfb8aa3b, v52
	v_mul_f32_e32 v55, 0xbfb8aa3b, v55
	v_mul_f32_e32 v58, 0xbfb8aa3b, v58
	v_exp_f32_e32 v48, v48
	v_exp_f32_e32 v51, v51
	v_exp_f32_e32 v54, v54
	v_exp_f32_e32 v57, v57
	v_exp_f32_e32 v49, v49
	v_exp_f32_e32 v52, v52
	v_exp_f32_e32 v55, v55
	v_exp_f32_e32 v58, v58
	v_lshlrev_b32_e32 v50, 16, v66
	v_lshlrev_b32_e32 v53, 16, v70
	v_lshlrev_b32_e32 v56, 16, v74
	v_lshlrev_b32_e32 v59, 16, v78
	v_add_f32_e32 v48, 1.0, v48
	v_add_f32_e32 v51, 1.0, v51
	v_add_f32_e32 v54, 1.0, v54
	v_add_f32_e32 v57, 1.0, v57
	v_add_f32_e32 v49, 1.0, v49
	v_add_f32_e32 v52, 1.0, v52
	v_add_f32_e32 v55, 1.0, v55
	v_add_f32_e32 v58, 1.0, v58
	v_rcp_f32_e32 v48, v48
	v_rcp_f32_e32 v51, v51
	v_rcp_f32_e32 v54, v54
	v_rcp_f32_e32 v57, v57
	v_rcp_f32_e32 v49, v49
	v_rcp_f32_e32 v52, v52
	v_rcp_f32_e32 v55, v55
	v_rcp_f32_e32 v58, v58
	v_mul_f32_e32 v48, v200, v48
	v_mul_f32_e32 v51, v200, v51
	v_mul_f32_e32 v54, v200, v54
	v_mul_f32_e32 v57, v200, v57
	v_mul_f32_e32 v49, v49, v50
	v_mul_f32_e32 v52, v52, v53
	v_mul_f32_e32 v55, v55, v56
	v_mul_f32_e32 v58, v58, v59
	v_mul_f32_e32 v48, 0x3fb8aa3b, v48
	v_mul_f32_e32 v51, 0x3fb8aa3b, v51
	v_mul_f32_e32 v54, 0x3fb8aa3b, v54
	v_mul_f32_e32 v57, 0x3fb8aa3b, v57
	v_exp_f32_e32 v48, v48
	v_exp_f32_e32 v51, v51
	v_exp_f32_e32 v54, v54
	v_exp_f32_e32 v57, v57
	v_sub_f32_e32 v50, 1.0, v48
	v_sub_f32_e32 v53, 1.0, v51
	v_sub_f32_e32 v56, 1.0, v54
	v_sub_f32_e32 v59, 1.0, v57
	v_add_f32_e32 v64, 1.0, v48
	v_add_f32_e32 v68, 1.0, v51
	v_add_f32_e32 v72, 1.0, v54
	v_add_f32_e32 v76, 1.0, v57
	v_mul_f32_e32 v50, v50, v64
	v_mul_f32_e32 v53, v53, v68
	v_mul_f32_e32 v56, v56, v72
	v_mul_f32_e32 v59, v59, v76
	v_max_f32_e32 v50, 0, v50
	v_max_f32_e32 v53, 0, v53
	v_max_f32_e32 v56, 0, v56
	v_max_f32_e32 v59, 0, v59
	v_sqrt_f32_e32 v50, v50
	v_sqrt_f32_e32 v53, v53
	v_sqrt_f32_e32 v56, v56
	v_sqrt_f32_e32 v59, v59
	v_mul_f32_e32 v49, v49, v50
	v_mul_f32_e32 v52, v52, v53
	v_mul_f32_e32 v55, v55, v56
	v_mul_f32_e32 v58, v58, v59
	v_fma_f32 v201, v201, v48, v49
	v_mov_b32_e32 v64, v201
	v_fma_f32 v201, v201, v51, v52
	v_mov_b32_e32 v68, v201
	v_fma_f32 v201, v201, v54, v55
; __device__ __forceinline__ float fast_sigmoid(float x) { return __builtin_amdgcn_rcpf(1.f + __builtin_amdgcn_exp2f(-1.4426950408889634f * x)); }
; __device__ __forceinline__ float bf2f(unsigned short h) { return __uint_as_float(((unsigned)h) << 16); }
; __device__ __forceinline__ float bflo(unsigned w) { return __uint_as_float(w << 16); }
; __device__ __forceinline__ float bfhi(unsigned w) { return __uint_as_float(w & 0xffff0000u); }
; __device__ __forceinline__ void scan_coef(float r, float i, float u, float sp8, float& a, float& b) { const float la = -sp8 * r; a = __expf(la); b = __builtin_amdgcn_sqrtf(fmaxf((1.f - a) * (1.f + a), 0.f)) * (i * u); }
; __global__ void __launch_bounds__(512) mega_fwd(Params P) {
;     ...
;                 for (int t = 0; t < 32; ++t) { const bf16_t* gp = XN + (size_t)(m0 + t) * 2048; const float u = bf2f(UC[(size_t)(m0 + t) * 512 + ch]);
;                     const unsigned g2 = *(const unsigned*)(gp + ch * 4);
;                     float a, b; scan_coef(pg8::fast_sigmoid(bflo(g2) + brf), pg8::fast_sigmoid(bfhi(g2) + bif), u, spf, a, b); hf = a * hf + b; hl[t * 512 + ch] = hf; }
	v_mov_b32_e32 v72, v201
	v_fma_f32 v201, v201, v57, v58
	v_mov_b32_e32 v76, v201
	global_load_dwordx2 v[144:145], v192, s[48:49]
	global_load_ushort v146, v8, s[50:51]
	global_load_ushort v147, v8, s[52:53]
	s_add_u32 s48, s48, 0x1000
	s_addc_u32 s49, s49, 0
	global_load_dwordx2 v[148:149], v192, s[48:49]
	global_load_ushort v150, v8, s[50:51] offset:1024
	global_load_ushort v151, v8, s[52:53] offset:1024
	s_add_u32 s48, s48, 0x1000
	s_addc_u32 s49, s49, 0
	global_load_dwordx2 v[152:153], v192, s[48:49]
	global_load_ushort v154, v8, s[50:51] offset:2048
	global_load_ushort v155, v8, s[52:53] offset:2048
	s_add_u32 s48, s48, 0x1000
	s_addc_u32 s49, s49, 0
	global_load_dwordx2 v[156:157], v192, s[48:49]
	global_load_ushort v158, v8, s[50:51] offset:3072
	global_load_ushort v159, v8, s[52:53] offset:3072
	s_add_u32 s48, s48, 0x1000
	s_addc_u32 s49, s49, 0
	s_add_u32 s50, s50, 0x1000
	s_addc_u32 s51, s51, 0
	s_add_u32 s52, s52, 0x1000
	s_addc_u32 s53, s53, 0
	v_lshlrev_b32_e32 v48, 16, v80
	v_lshlrev_b32_e32 v51, 16, v84
	v_lshlrev_b32_e32 v54, 16, v88
	v_lshlrev_b32_e32 v57, 16, v92
	v_and_b32_e32 v49, 0xffff0000, v80
	v_and_b32_e32 v52, 0xffff0000, v84
	v_and_b32_e32 v55, 0xffff0000, v88
	v_and_b32_e32 v58, 0xffff0000, v92
	v_add_f32_e32 v48, v198, v48
	v_add_f32_e32 v51, v198, v51
	v_add_f32_e32 v54, v198, v54
	v_add_f32_e32 v57, v198, v57
	v_add_f32_e32 v49, v199, v49
	v_add_f32_e32 v52, v199, v52
	v_add_f32_e32 v55, v199, v55
	v_add_f32_e32 v58, v199, v58
	v_mul_f32_e32 v48, 0xbfb8aa3b, v48
	v_mul_f32_e32 v51, 0xbfb8aa3b, v51
	v_mul_f32_e32 v54, 0xbfb8aa3b, v54
	v_mul_f32_e32 v57, 0xbfb8aa3b, v57
	v_mul_f32_e32 v49, 0xbfb8aa3b, v49
	v_mul_f32_e32 v52, 0xbfb8aa3b, v52
	v_mul_f32_e32 v55, 0xbfb8aa3b, v55
	v_mul_f32_e32 v58, 0xbfb8aa3b, v58
	v_exp_f32_e32 v48, v48
	v_exp_f32_e32 v51, v51
	v_exp_f32_e32 v54, v54
	v_exp_f32_e32 v57, v57
	v_exp_f32_e32 v49, v49
	v_exp_f32_e32 v52, v52
	v_exp_f32_e32 v55, v55
	v_exp_f32_e32 v58, v58
	v_lshlrev_b32_e32 v50, 16, v82
	v_lshlrev_b32_e32 v53, 16, v86
	v_lshlrev_b32_e32 v56, 16, v90
	v_lshlrev_b32_e32 v59, 16, v94
	v_add_f32_e32 v48, 1.0, v48
	v_add_f32_e32 v51, 1.0, v51
	v_add_f32_e32 v54, 1.0, v54
	v_add_f32_e32 v57, 1.0, v57
	v_add_f32_e32 v49, 1.0, v49
	v_add_f32_e32 v52, 1.0, v52
	v_add_f32_e32 v55, 1.0, v55
	v_add_f32_e32 v58, 1.0, v58
	v_rcp_f32_e32 v48, v48
	v_rcp_f32_e32 v51, v51
	v_rcp_f32_e32 v54, v54
	v_rcp_f32_e32 v57, v57
	v_rcp_f32_e32 v49, v49
	v_rcp_f32_e32 v52, v52
	v_rcp_f32_e32 v55, v55
	v_rcp_f32_e32 v58, v58
	v_mul_f32_e32 v48, v200, v48
	v_mul_f32_e32 v51, v200, v51
	v_mul_f32_e32 v54, v200, v54
	v_mul_f32_e32 v57, v200, v57
	v_mul_f32_e32 v49, v49, v50
	v_mul_f32_e32 v52, v52, v53
	v_mul_f32_e32 v55, v55, v56
	v_mul_f32_e32 v58, v58, v59
	v_mul_f32_e32 v48, 0x3fb8aa3b, v48
	v_mul_f32_e32 v51, 0x3fb8aa3b, v51
	v_mul_f32_e32 v54, 0x3fb8aa3b, v54
	v_mul_f32_e32 v57, 0x3fb8aa3b, v57
	v_exp_f32_e32 v48, v48
	v_exp_f32_e32 v51, v51
	v_exp_f32_e32 v54, v54
	v_exp_f32_e32 v57, v57
	v_sub_f32_e32 v50, 1.0, v48
	v_sub_f32_e32 v53, 1.0, v51
	v_sub_f32_e32 v56, 1.0, v54
	v_sub_f32_e32 v59, 1.0, v57
	v_add_f32_e32 v80, 1.0, v48
	v_add_f32_e32 v84, 1.0, v51
	v_add_f32_e32 v88, 1.0, v54
	v_add_f32_e32 v92, 1.0, v57
	v_mul_f32_e32 v50, v50, v80
	v_mul_f32_e32 v53, v53, v84
	v_mul_f32_e32 v56, v56, v88
	v_mul_f32_e32 v59, v59, v92
	v_max_f32_e32 v50, 0, v50
	v_max_f32_e32 v53, 0, v53
	v_max_f32_e32 v56, 0, v56
	v_max_f32_e32 v59, 0, v59
	v_sqrt_f32_e32 v50, v50
	v_sqrt_f32_e32 v53, v53
	v_sqrt_f32_e32 v56, v56
	v_sqrt_f32_e32 v59, v59
	v_mul_f32_e32 v49, v49, v50
	v_mul_f32_e32 v52, v52, v53
	v_mul_f32_e32 v55, v55, v56
	v_mul_f32_e32 v58, v58, v59
	v_fma_f32 v201, v201, v48, v49
	v_mov_b32_e32 v80, v201
	v_fma_f32 v201, v201, v51, v52
	v_mov_b32_e32 v84, v201
	v_fma_f32 v201, v201, v54, v55
	v_mov_b32_e32 v88, v201
	v_fma_f32 v201, v201, v57, v58
	v_mov_b32_e32 v92, v201
	global_load_dwordx2 v[160:161], v192, s[48:49]
	global_load_ushort v162, v8, s[50:51]
	global_load_ushort v163, v8, s[52:53]
	s_add_u32 s48, s48, 0x1000
	s_addc_u32 s49, s49, 0
	global_load_dwordx2 v[164:165], v192, s[48:49]
	global_load_ushort v166, v8, s[50:51] offset:1024
	global_load_ushort v167, v8, s[52:53] offset:1024
	s_add_u32 s48, s48, 0x1000
	s_addc_u32 s49, s49, 0
	global_load_dwordx2 v[168:169], v192, s[48:49]
	global_load_ushort v170, v8, s[50:51] offset:2048
	global_load_ushort v171, v8, s[52:53] offset:2048
	s_add_u32 s48, s48, 0x1000
	s_addc_u32 s49, s49, 0
	global_load_dwordx2 v[172:173], v192, s[48:49]
	global_load_ushort v174, v8, s[50:51] offset:3072
	global_load_ushort v175, v8, s[52:53] offset:3072
	s_add_u32 s48, s48, 0x1000
	s_addc_u32 s49, s49, 0
	s_add_u32 s50, s50, 0x1000
	s_addc_u32 s51, s51, 0
	s_add_u32 s52, s52, 0x1000
	s_addc_u32 s53, s53, 0
	v_lshlrev_b32_e32 v48, 16, v96
	v_lshlrev_b32_e32 v51, 16, v100
	v_lshlrev_b32_e32 v54, 16, v104
	v_lshlrev_b32_e32 v57, 16, v108
	v_and_b32_e32 v49, 0xffff0000, v96
	v_and_b32_e32 v52, 0xffff0000, v100
	v_and_b32_e32 v55, 0xffff0000, v104
	v_and_b32_e32 v58, 0xffff0000, v108
	v_add_f32_e32 v48, v198, v48
	v_add_f32_e32 v51, v198, v51
	v_add_f32_e32 v54, v198, v54
	v_add_f32_e32 v57, v198, v57
	v_add_f32_e32 v49, v199, v49
	v_add_f32_e32 v52, v199, v52
	v_add_f32_e32 v55, v199, v55
	v_add_f32_e32 v58, v199, v58
	v_mul_f32_e32 v48, 0xbfb8aa3b, v48
	v_mul_f32_e32 v51, 0xbfb8aa3b, v51
	v_mul_f32_e32 v54, 0xbfb8aa3b, v54
	v_mul_f32_e32 v57, 0xbfb8aa3b, v57
	v_mul_f32_e32 v49, 0xbfb8aa3b, v49
	v_mul_f32_e32 v52, 0xbfb8aa3b, v52
	v_mul_f32_e32 v55, 0xbfb8aa3b, v55
	v_mul_f32_e32 v58, 0xbfb8aa3b, v58
	v_exp_f32_e32 v48, v48
	v_exp_f32_e32 v51, v51
; __device__ __forceinline__ float fast_sigmoid(float x) { return __builtin_amdgcn_rcpf(1.f + __builtin_amdgcn_exp2f(-1.4426950408889634f * x)); }
; __device__ __forceinline__ float bf2f(unsigned short h) { return __uint_as_float(((unsigned)h) << 16); }
; __device__ __forceinline__ float bflo(unsigned w) { return __uint_as_float(w << 16); }
; __device__ __forceinline__ float bfhi(unsigned w) { return __uint_as_float(w & 0xffff0000u); }
; __device__ __forceinline__ void scan_coef(float r, float i, float u, float sp8, float& a, float& b) { const float la = -sp8 * r; a = __expf(la); b = __builtin_amdgcn_sqrtf(fmaxf((1.f - a) * (1.f + a), 0.f)) * (i * u); }
; __global__ void __launch_bounds__(512) mega_fwd(Params P) {
;     ...
;                 for (int t = 0; t < 32; ++t) { const bf16_t* gp = XN + (size_t)(m0 + t) * 2048; const float u = bf2f(UC[(size_t)(m0 + t) * 512 + ch]);
;                     const unsigned g2 = *(const unsigned*)(gp + ch * 4);
;                     float a, b; scan_coef(pg8::fast_sigmoid(bflo(g2) + brf), pg8::fast_sigmoid(bfhi(g2) + bif), u, spf, a, b); hf = a * hf + b; hl[t * 512 + ch] = hf; }
	v_exp_f32_e32 v54, v54
	v_exp_f32_e32 v57, v57
	v_exp_f32_e32 v49, v49
	v_exp_f32_e32 v52, v52
	v_exp_f32_e32 v55, v55
	v_exp_f32_e32 v58, v58
	v_lshlrev_b32_e32 v50, 16, v98
	v_lshlrev_b32_e32 v53, 16, v102
	v_lshlrev_b32_e32 v56, 16, v106
	v_lshlrev_b32_e32 v59, 16, v110
	v_add_f32_e32 v48, 1.0, v48
	v_add_f32_e32 v51, 1.0, v51
	v_add_f32_e32 v54, 1.0, v54
	v_add_f32_e32 v57, 1.0, v57
	v_add_f32_e32 v49, 1.0, v49
	v_add_f32_e32 v52, 1.0, v52
	v_add_f32_e32 v55, 1.0, v55
	v_add_f32_e32 v58, 1.0, v58
	v_rcp_f32_e32 v48, v48
	v_rcp_f32_e32 v51, v51
	v_rcp_f32_e32 v54, v54
	v_rcp_f32_e32 v57, v57
	v_rcp_f32_e32 v49, v49
	v_rcp_f32_e32 v52, v52
	v_rcp_f32_e32 v55, v55
	v_rcp_f32_e32 v58, v58
	v_mul_f32_e32 v48, v200, v48
	v_mul_f32_e32 v51, v200, v51
	v_mul_f32_e32 v54, v200, v54
	v_mul_f32_e32 v57, v200, v57
	v_mul_f32_e32 v49, v49, v50
	v_mul_f32_e32 v52, v52, v53
	v_mul_f32_e32 v55, v55, v56
	v_mul_f32_e32 v58, v58, v59
	v_mul_f32_e32 v48, 0x3fb8aa3b, v48
	v_mul_f32_e32 v51, 0x3fb8aa3b, v51
	v_mul_f32_e32 v54, 0x3fb8aa3b, v54
	v_mul_f32_e32 v57, 0x3fb8aa3b, v57
	v_exp_f32_e32 v48, v48
	v_exp_f32_e32 v51, v51
	v_exp_f32_e32 v54, v54
	v_exp_f32_e32 v57, v57
	v_sub_f32_e32 v50, 1.0, v48
	v_sub_f32_e32 v53, 1.0, v51
	v_sub_f32_e32 v56, 1.0, v54
	v_sub_f32_e32 v59, 1.0, v57
	v_add_f32_e32 v96, 1.0, v48
	v_add_f32_e32 v100, 1.0, v51
	v_add_f32_e32 v104, 1.0, v54
	v_add_f32_e32 v108, 1.0, v57
	v_mul_f32_e32 v50, v50, v96
	v_mul_f32_e32 v53, v53, v100
	v_mul_f32_e32 v56, v56, v104
	v_mul_f32_e32 v59, v59, v108
	v_max_f32_e32 v50, 0, v50
	v_max_f32_e32 v53, 0, v53
	v_max_f32_e32 v56, 0, v56
	v_max_f32_e32 v59, 0, v59
	v_sqrt_f32_e32 v50, v50
	v_sqrt_f32_e32 v53, v53
	v_sqrt_f32_e32 v56, v56
	v_sqrt_f32_e32 v59, v59
	v_mul_f32_e32 v49, v49, v50
	v_mul_f32_e32 v52, v52, v53
	v_mul_f32_e32 v55, v55, v56
	v_mul_f32_e32 v58, v58, v59
	v_fma_f32 v201, v201, v48, v49
	v_mov_b32_e32 v96, v201
	v_fma_f32 v201, v201, v51, v52
	v_mov_b32_e32 v100, v201
	v_fma_f32 v201, v201, v54, v55
	v_mov_b32_e32 v104, v201
	v_fma_f32 v201, v201, v57, v58
	v_mov_b32_e32 v108, v201
	global_load_dwordx2 v[176:177], v192, s[48:49]
	global_load_ushort v178, v8, s[50:51]
	global_load_ushort v179, v8, s[52:53]
	s_add_u32 s48, s48, 0x1000
	s_addc_u32 s49, s49, 0
	global_load_dwordx2 v[180:181], v192, s[48:49]
	global_load_ushort v182, v8, s[50:51] offset:1024
	global_load_ushort v183, v8, s[52:53] offset:1024
	s_add_u32 s48, s48, 0x1000
	s_addc_u32 s49, s49, 0
	global_load_dwordx2 v[184:185], v192, s[48:49]
	global_load_ushort v186, v8, s[50:51] offset:2048
	global_load_ushort v187, v8, s[52:53] offset:2048
	s_add_u32 s48, s48, 0x1000
	s_addc_u32 s49, s49, 0
	global_load_dwordx2 v[188:189], v192, s[48:49]
	global_load_ushort v190, v8, s[50:51] offset:3072
	global_load_ushort v191, v8, s[52:53] offset:3072
	s_add_u32 s48, s48, 0x1000
	s_addc_u32 s49, s49, 0
	s_add_u32 s50, s50, 0x1000
	s_addc_u32 s51, s51, 0
	s_add_u32 s52, s52, 0x1000
	s_addc_u32 s53, s53, 0
	v_lshlrev_b32_e32 v48, 16, v112
	v_lshlrev_b32_e32 v51, 16, v116
	v_lshlrev_b32_e32 v54, 16, v120
	v_lshlrev_b32_e32 v57, 16, v124
	v_and_b32_e32 v49, 0xffff0000, v112
	v_and_b32_e32 v52, 0xffff0000, v116
	v_and_b32_e32 v55, 0xffff0000, v120
	v_and_b32_e32 v58, 0xffff0000, v124
	v_add_f32_e32 v48, v198, v48
	v_add_f32_e32 v51, v198, v51
	v_add_f32_e32 v54, v198, v54
	v_add_f32_e32 v57, v198, v57
	v_add_f32_e32 v49, v199, v49
	v_add_f32_e32 v52, v199, v52
	v_add_f32_e32 v55, v199, v55
	v_add_f32_e32 v58, v199, v58
	v_mul_f32_e32 v48, 0xbfb8aa3b, v48
	v_mul_f32_e32 v51, 0xbfb8aa3b, v51
	v_mul_f32_e32 v54, 0xbfb8aa3b, v54
	v_mul_f32_e32 v57, 0xbfb8aa3b, v57
	v_mul_f32_e32 v49, 0xbfb8aa3b, v49
	v_mul_f32_e32 v52, 0xbfb8aa3b, v52
	v_mul_f32_e32 v55, 0xbfb8aa3b, v55
	v_mul_f32_e32 v58, 0xbfb8aa3b, v58
	v_exp_f32_e32 v48, v48
	v_exp_f32_e32 v51, v51
	v_exp_f32_e32 v54, v54
	v_exp_f32_e32 v57, v57
	v_exp_f32_e32 v49, v49
	v_exp_f32_e32 v52, v52
	v_exp_f32_e32 v55, v55
	v_exp_f32_e32 v58, v58
	v_lshlrev_b32_e32 v50, 16, v114
	v_lshlrev_b32_e32 v53, 16, v118
	v_lshlrev_b32_e32 v56, 16, v122
	v_lshlrev_b32_e32 v59, 16, v126
	v_add_f32_e32 v48, 1.0, v48
	v_add_f32_e32 v51, 1.0, v51
	v_add_f32_e32 v54, 1.0, v54
	v_add_f32_e32 v57, 1.0, v57
	v_add_f32_e32 v49, 1.0, v49
	v_add_f32_e32 v52, 1.0, v52
	v_add_f32_e32 v55, 1.0, v55
	v_add_f32_e32 v58, 1.0, v58
	v_rcp_f32_e32 v48, v48
	v_rcp_f32_e32 v51, v51
	v_rcp_f32_e32 v54, v54
	v_rcp_f32_e32 v57, v57
	v_rcp_f32_e32 v49, v49
	v_rcp_f32_e32 v52, v52
	v_rcp_f32_e32 v55, v55
	v_rcp_f32_e32 v58, v58
	v_mul_f32_e32 v48, v200, v48
	v_mul_f32_e32 v51, v200, v51
	v_mul_f32_e32 v54, v200, v54
	v_mul_f32_e32 v57, v200, v57
	v_mul_f32_e32 v49, v49, v50
	v_mul_f32_e32 v52, v52, v53
	v_mul_f32_e32 v55, v55, v56
	v_mul_f32_e32 v58, v58, v59
	v_mul_f32_e32 v48, 0x3fb8aa3b, v48
	v_mul_f32_e32 v51, 0x3fb8aa3b, v51
	v_mul_f32_e32 v54, 0x3fb8aa3b, v54
	v_mul_f32_e32 v57, 0x3fb8aa3b, v57
	v_exp_f32_e32 v48, v48
	v_exp_f32_e32 v51, v51
	v_exp_f32_e32 v54, v54
	v_exp_f32_e32 v57, v57
	v_sub_f32_e32 v50, 1.0, v48
	v_sub_f32_e32 v53, 1.0, v51
	v_sub_f32_e32 v56, 1.0, v54
	v_sub_f32_e32 v59, 1.0, v57
	v_add_f32_e32 v112, 1.0, v48
	v_add_f32_e32 v116, 1.0, v51
	v_add_f32_e32 v120, 1.0, v54
	v_add_f32_e32 v124, 1.0, v57
	v_mul_f32_e32 v50, v50, v112
	v_mul_f32_e32 v53, v53, v116
	v_mul_f32_e32 v56, v56, v120
	v_mul_f32_e32 v59, v59, v124
	v_max_f32_e32 v50, 0, v50
	v_max_f32_e32 v53, 0, v53
	v_max_f32_e32 v56, 0, v56
	v_max_f32_e32 v59, 0, v59
	v_sqrt_f32_e32 v50, v50
	v_sqrt_f32_e32 v53, v53
	v_sqrt_f32_e32 v56, v56
	v_sqrt_f32_e32 v59, v59
	v_mul_f32_e32 v49, v49, v50
	v_mul_f32_e32 v52, v52, v53
	v_mul_f32_e32 v55, v55, v56
	v_mul_f32_e32 v58, v58, v59
	v_fma_f32 v201, v201, v48, v49
	v_mov_b32_e32 v112, v201
	v_fma_f32 v201, v201, v51, v52
	v_mov_b32_e32 v116, v201
	v_fma_f32 v201, v201, v54, v55
	v_mov_b32_e32 v120, v201
	v_fma_f32 v201, v201, v57, v58
	v_mov_b32_e32 v124, v201
	s_waitcnt vmcnt(36)
; __device__ __forceinline__ float fast_sigmoid(float x) { return __builtin_amdgcn_rcpf(1.f + __builtin_amdgcn_exp2f(-1.4426950408889634f * x)); }
; __device__ __forceinline__ float bf2f(unsigned short h) { return __uint_as_float(((unsigned)h) << 16); }
; __device__ __forceinline__ float bflo(unsigned w) { return __uint_as_float(w << 16); }
; __device__ __forceinline__ float bfhi(unsigned w) { return __uint_as_float(w & 0xffff0000u); }
; __device__ __forceinline__ void scan_coef(float r, float i, float u, float sp8, float& a, float& b) { const float la = -sp8 * r; a = __expf(la); b = __builtin_amdgcn_sqrtf(fmaxf((1.f - a) * (1.f + a), 0.f)) * (i * u); }
; __global__ void __launch_bounds__(512) mega_fwd(Params P) {
;     ...
;                 for (int t = 0; t < 32; ++t) { const bf16_t* gp = XN + (size_t)(m0 + t) * 2048; const float u = bf2f(UC[(size_t)(m0 + t) * 512 + ch]);
;                     const unsigned g2 = *(const unsigned*)(gp + ch * 4);
;                     float a, b; scan_coef(pg8::fast_sigmoid(bflo(g2) + brf), pg8::fast_sigmoid(bfhi(g2) + bif), u, spf, a, b); hf = a * hf + b; hl[t * 512 + ch] = hf; }
	v_lshlrev_b32_e32 v48, 16, v128
	v_lshlrev_b32_e32 v51, 16, v132
	v_lshlrev_b32_e32 v54, 16, v136
	v_lshlrev_b32_e32 v57, 16, v140
	v_and_b32_e32 v49, 0xffff0000, v128
	v_and_b32_e32 v52, 0xffff0000, v132
	v_and_b32_e32 v55, 0xffff0000, v136
	v_and_b32_e32 v58, 0xffff0000, v140
	v_add_f32_e32 v48, v198, v48
	v_add_f32_e32 v51, v198, v51
	v_add_f32_e32 v54, v198, v54
	v_add_f32_e32 v57, v198, v57
	v_add_f32_e32 v49, v199, v49
	v_add_f32_e32 v52, v199, v52
	v_add_f32_e32 v55, v199, v55
	v_add_f32_e32 v58, v199, v58
	v_mul_f32_e32 v48, 0xbfb8aa3b, v48
	v_mul_f32_e32 v51, 0xbfb8aa3b, v51
	v_mul_f32_e32 v54, 0xbfb8aa3b, v54
	v_mul_f32_e32 v57, 0xbfb8aa3b, v57
	v_mul_f32_e32 v49, 0xbfb8aa3b, v49
	v_mul_f32_e32 v52, 0xbfb8aa3b, v52
	v_mul_f32_e32 v55, 0xbfb8aa3b, v55
	v_mul_f32_e32 v58, 0xbfb8aa3b, v58
	v_exp_f32_e32 v48, v48
	v_exp_f32_e32 v51, v51
	v_exp_f32_e32 v54, v54
	v_exp_f32_e32 v57, v57
	v_exp_f32_e32 v49, v49
	v_exp_f32_e32 v52, v52
	v_exp_f32_e32 v55, v55
	v_exp_f32_e32 v58, v58
	v_lshlrev_b32_e32 v50, 16, v130
	v_lshlrev_b32_e32 v53, 16, v134
	v_lshlrev_b32_e32 v56, 16, v138
	v_lshlrev_b32_e32 v59, 16, v142
	v_add_f32_e32 v48, 1.0, v48
	v_add_f32_e32 v51, 1.0, v51
	v_add_f32_e32 v54, 1.0, v54
	v_add_f32_e32 v57, 1.0, v57
	v_add_f32_e32 v49, 1.0, v49
	v_add_f32_e32 v52, 1.0, v52
	v_add_f32_e32 v55, 1.0, v55
	v_add_f32_e32 v58, 1.0, v58
	v_rcp_f32_e32 v48, v48
	v_rcp_f32_e32 v51, v51
	v_rcp_f32_e32 v54, v54
	v_rcp_f32_e32 v57, v57
	v_rcp_f32_e32 v49, v49
	v_rcp_f32_e32 v52, v52
	v_rcp_f32_e32 v55, v55
	v_rcp_f32_e32 v58, v58
	v_mul_f32_e32 v48, v200, v48
	v_mul_f32_e32 v51, v200, v51
	v_mul_f32_e32 v54, v200, v54
	v_mul_f32_e32 v57, v200, v57
	v_mul_f32_e32 v49, v49, v50
	v_mul_f32_e32 v52, v52, v53
	v_mul_f32_e32 v55, v55, v56
	v_mul_f32_e32 v58, v58, v59
	v_mul_f32_e32 v48, 0x3fb8aa3b, v48
	v_mul_f32_e32 v51, 0x3fb8aa3b, v51
	v_mul_f32_e32 v54, 0x3fb8aa3b, v54
	v_mul_f32_e32 v57, 0x3fb8aa3b, v57
	v_exp_f32_e32 v48, v48
	v_exp_f32_e32 v51, v51
	v_exp_f32_e32 v54, v54
	v_exp_f32_e32 v57, v57
	v_sub_f32_e32 v50, 1.0, v48
	v_sub_f32_e32 v53, 1.0, v51
	v_sub_f32_e32 v56, 1.0, v54
	v_sub_f32_e32 v59, 1.0, v57
	v_add_f32_e32 v128, 1.0, v48
	v_add_f32_e32 v132, 1.0, v51
	v_add_f32_e32 v136, 1.0, v54
	v_add_f32_e32 v140, 1.0, v57
	v_mul_f32_e32 v50, v50, v128
	v_mul_f32_e32 v53, v53, v132
	v_mul_f32_e32 v56, v56, v136
	v_mul_f32_e32 v59, v59, v140
	v_max_f32_e32 v50, 0, v50
	v_max_f32_e32 v53, 0, v53
	v_max_f32_e32 v56, 0, v56
	v_max_f32_e32 v59, 0, v59
	v_sqrt_f32_e32 v50, v50
	v_sqrt_f32_e32 v53, v53
	v_sqrt_f32_e32 v56, v56
	v_sqrt_f32_e32 v59, v59
	v_mul_f32_e32 v49, v49, v50
	v_mul_f32_e32 v52, v52, v53
	v_mul_f32_e32 v55, v55, v56
	v_mul_f32_e32 v58, v58, v59
	v_fma_f32 v201, v201, v48, v49
	v_mov_b32_e32 v128, v201
	v_fma_f32 v201, v201, v51, v52
	v_mov_b32_e32 v132, v201
	v_fma_f32 v201, v201, v54, v55
	v_mov_b32_e32 v136, v201
	v_fma_f32 v201, v201, v57, v58
	v_mov_b32_e32 v140, v201
	s_waitcnt vmcnt(24)
	v_lshlrev_b32_e32 v48, 16, v144
	v_lshlrev_b32_e32 v51, 16, v148
	v_lshlrev_b32_e32 v54, 16, v152
	v_lshlrev_b32_e32 v57, 16, v156
	v_and_b32_e32 v49, 0xffff0000, v144
	v_and_b32_e32 v52, 0xffff0000, v148
	v_and_b32_e32 v55, 0xffff0000, v152
	v_and_b32_e32 v58, 0xffff0000, v156
	v_add_f32_e32 v48, v198, v48
	v_add_f32_e32 v51, v198, v51
	v_add_f32_e32 v54, v198, v54
	v_add_f32_e32 v57, v198, v57
	v_add_f32_e32 v49, v199, v49
	v_add_f32_e32 v52, v199, v52
	v_add_f32_e32 v55, v199, v55
	v_add_f32_e32 v58, v199, v58
	v_mul_f32_e32 v48, 0xbfb8aa3b, v48
	v_mul_f32_e32 v51, 0xbfb8aa3b, v51
	v_mul_f32_e32 v54, 0xbfb8aa3b, v54
	v_mul_f32_e32 v57, 0xbfb8aa3b, v57
	v_mul_f32_e32 v49, 0xbfb8aa3b, v49
	v_mul_f32_e32 v52, 0xbfb8aa3b, v52
	v_mul_f32_e32 v55, 0xbfb8aa3b, v55
	v_mul_f32_e32 v58, 0xbfb8aa3b, v58
	v_exp_f32_e32 v48, v48
	v_exp_f32_e32 v51, v51
	v_exp_f32_e32 v54, v54
	v_exp_f32_e32 v57, v57
	v_exp_f32_e32 v49, v49
	v_exp_f32_e32 v52, v52
	v_exp_f32_e32 v55, v55
	v_exp_f32_e32 v58, v58
	v_lshlrev_b32_e32 v50, 16, v146
	v_lshlrev_b32_e32 v53, 16, v150
	v_lshlrev_b32_e32 v56, 16, v154
	v_lshlrev_b32_e32 v59, 16, v158
	v_add_f32_e32 v48, 1.0, v48
	v_add_f32_e32 v51, 1.0, v51
	v_add_f32_e32 v54, 1.0, v54
	v_add_f32_e32 v57, 1.0, v57
	v_add_f32_e32 v49, 1.0, v49
	v_add_f32_e32 v52, 1.0, v52
	v_add_f32_e32 v55, 1.0, v55
	v_add_f32_e32 v58, 1.0, v58
	v_rcp_f32_e32 v48, v48
	v_rcp_f32_e32 v51, v51
	v_rcp_f32_e32 v54, v54
	v_rcp_f32_e32 v57, v57
	v_rcp_f32_e32 v49, v49
	v_rcp_f32_e32 v52, v52
	v_rcp_f32_e32 v55, v55
	v_rcp_f32_e32 v58, v58
	v_mul_f32_e32 v48, v200, v48
	v_mul_f32_e32 v51, v200, v51
	v_mul_f32_e32 v54, v200, v54
	v_mul_f32_e32 v57, v200, v57
	v_mul_f32_e32 v49, v49, v50
	v_mul_f32_e32 v52, v52, v53
	v_mul_f32_e32 v55, v55, v56
	v_mul_f32_e32 v58, v58, v59
	v_mul_f32_e32 v48, 0x3fb8aa3b, v48
	v_mul_f32_e32 v51, 0x3fb8aa3b, v51
	v_mul_f32_e32 v54, 0x3fb8aa3b, v54
	v_mul_f32_e32 v57, 0x3fb8aa3b, v57
	v_exp_f32_e32 v48, v48
	v_exp_f32_e32 v51, v51
	v_exp_f32_e32 v54, v54
	v_exp_f32_e32 v57, v57
	v_sub_f32_e32 v50, 1.0, v48
	v_sub_f32_e32 v53, 1.0, v51
	v_sub_f32_e32 v56, 1.0, v54
	v_sub_f32_e32 v59, 1.0, v57
	v_add_f32_e32 v144, 1.0, v48
	v_add_f32_e32 v148, 1.0, v51
	v_add_f32_e32 v152, 1.0, v54
	v_add_f32_e32 v156, 1.0, v57
	v_mul_f32_e32 v50, v50, v144
	v_mul_f32_e32 v53, v53, v148
	v_mul_f32_e32 v56, v56, v152
	v_mul_f32_e32 v59, v59, v156
	v_max_f32_e32 v50, 0, v50
	v_max_f32_e32 v53, 0, v53
	v_max_f32_e32 v56, 0, v56
	v_max_f32_e32 v59, 0, v59
	v_sqrt_f32_e32 v50, v50
	v_sqrt_f32_e32 v53, v53
	v_sqrt_f32_e32 v56, v56
	v_sqrt_f32_e32 v59, v59
	v_mul_f32_e32 v49, v49, v50
	v_mul_f32_e32 v52, v52, v53
	v_mul_f32_e32 v55, v55, v56
	v_mul_f32_e32 v58, v58, v59
	v_fma_f32 v201, v201, v48, v49
	v_mov_b32_e32 v144, v201
	v_fma_f32 v201, v201, v51, v52
	v_mov_b32_e32 v148, v201
	v_fma_f32 v201, v201, v54, v55
	v_mov_b32_e32 v152, v201
	v_fma_f32 v201, v201, v57, v58
	v_mov_b32_e32 v156, v201
	s_waitcnt vmcnt(12)
; __device__ __forceinline__ float fast_sigmoid(float x) { return __builtin_amdgcn_rcpf(1.f + __builtin_amdgcn_exp2f(-1.4426950408889634f * x)); }
; __device__ __forceinline__ float bf2f(unsigned short h) { return __uint_as_float(((unsigned)h) << 16); }
; __device__ __forceinline__ float bflo(unsigned w) { return __uint_as_float(w << 16); }
; __device__ __forceinline__ float bfhi(unsigned w) { return __uint_as_float(w & 0xffff0000u); }
; __device__ __forceinline__ void scan_coef(float r, float i, float u, float sp8, float& a, float& b) { const float la = -sp8 * r; a = __expf(la); b = __builtin_amdgcn_sqrtf(fmaxf((1.f - a) * (1.f + a), 0.f)) * (i * u); }
; __global__ void __launch_bounds__(512) mega_fwd(Params P) {
;     ...
;                 for (int t = 0; t < 32; ++t) { const bf16_t* gp = XN + (size_t)(m0 + t) * 2048; const float u = bf2f(UC[(size_t)(m0 + t) * 512 + ch]);
;                     const unsigned g2 = *(const unsigned*)(gp + ch * 4);
;                     float a, b; scan_coef(pg8::fast_sigmoid(bflo(g2) + brf), pg8::fast_sigmoid(bfhi(g2) + bif), u, spf, a, b); hf = a * hf + b; hl[t * 512 + ch] = hf; }
;                 for (int tb = 28; tb >= 0; tb -= 4) { float rr[4], ii[4], uu[4], gg[4];
; #pragma unroll
;                     for (int k = 0; k < 4; ++k) { const bf16_t* gp = XN + (size_t)(m0 + tb + k) * 2048; { const unsigned g2 = *(const unsigned*)(gp + ch * 4 + 2); rr[k] = bflo(g2); ii[k] = bfhi(g2); }
;                         uu[k] = bf2f(UC[(size_t)(m0 + tb + k) * 512 + ch]); gg[k] = bf2f(GT[(size_t)(m0 + tb + k) * 512 + ch]); }
; #pragma unroll
;                     for (int k = 3; k >= 0; --k) { float a, b; scan_coef(pg8::fast_sigmoid(rr[k] + brb), pg8::fast_sigmoid(ii[k] + bib), uu[k], spb, a, b); hb = a * hb + b;
	v_lshlrev_b32_e32 v48, 16, v160
	v_lshlrev_b32_e32 v51, 16, v164
	v_lshlrev_b32_e32 v54, 16, v168
	v_lshlrev_b32_e32 v57, 16, v172
	v_and_b32_e32 v49, 0xffff0000, v160
	v_and_b32_e32 v52, 0xffff0000, v164
	v_and_b32_e32 v55, 0xffff0000, v168
	v_and_b32_e32 v58, 0xffff0000, v172
	v_add_f32_e32 v48, v198, v48
	v_add_f32_e32 v51, v198, v51
	v_add_f32_e32 v54, v198, v54
	v_add_f32_e32 v57, v198, v57
	v_add_f32_e32 v49, v199, v49
	v_add_f32_e32 v52, v199, v52
	v_add_f32_e32 v55, v199, v55
	v_add_f32_e32 v58, v199, v58
	v_mul_f32_e32 v48, 0xbfb8aa3b, v48
	v_mul_f32_e32 v51, 0xbfb8aa3b, v51
	v_mul_f32_e32 v54, 0xbfb8aa3b, v54
	v_mul_f32_e32 v57, 0xbfb8aa3b, v57
	v_mul_f32_e32 v49, 0xbfb8aa3b, v49
	v_mul_f32_e32 v52, 0xbfb8aa3b, v52
	v_mul_f32_e32 v55, 0xbfb8aa3b, v55
	v_mul_f32_e32 v58, 0xbfb8aa3b, v58
	v_exp_f32_e32 v48, v48
	v_exp_f32_e32 v51, v51
	v_exp_f32_e32 v54, v54
	v_exp_f32_e32 v57, v57
	v_exp_f32_e32 v49, v49
	v_exp_f32_e32 v52, v52
	v_exp_f32_e32 v55, v55
	v_exp_f32_e32 v58, v58
	v_lshlrev_b32_e32 v50, 16, v162
	v_lshlrev_b32_e32 v53, 16, v166
	v_lshlrev_b32_e32 v56, 16, v170
	v_lshlrev_b32_e32 v59, 16, v174
	v_add_f32_e32 v48, 1.0, v48
	v_add_f32_e32 v51, 1.0, v51
	v_add_f32_e32 v54, 1.0, v54
	v_add_f32_e32 v57, 1.0, v57
	v_add_f32_e32 v49, 1.0, v49
	v_add_f32_e32 v52, 1.0, v52
	v_add_f32_e32 v55, 1.0, v55
	v_add_f32_e32 v58, 1.0, v58
	v_rcp_f32_e32 v48, v48
	v_rcp_f32_e32 v51, v51
	v_rcp_f32_e32 v54, v54
	v_rcp_f32_e32 v57, v57
	v_rcp_f32_e32 v49, v49
	v_rcp_f32_e32 v52, v52
	v_rcp_f32_e32 v55, v55
	v_rcp_f32_e32 v58, v58
	v_mul_f32_e32 v48, v200, v48
	v_mul_f32_e32 v51, v200, v51
	v_mul_f32_e32 v54, v200, v54
	v_mul_f32_e32 v57, v200, v57
	v_mul_f32_e32 v49, v49, v50
	v_mul_f32_e32 v52, v52, v53
	v_mul_f32_e32 v55, v55, v56
	v_mul_f32_e32 v58, v58, v59
	v_mul_f32_e32 v48, 0x3fb8aa3b, v48
	v_mul_f32_e32 v51, 0x3fb8aa3b, v51
	v_mul_f32_e32 v54, 0x3fb8aa3b, v54
	v_mul_f32_e32 v57, 0x3fb8aa3b, v57
	v_exp_f32_e32 v48, v48
	v_exp_f32_e32 v51, v51
	v_exp_f32_e32 v54, v54
	v_exp_f32_e32 v57, v57
	v_sub_f32_e32 v50, 1.0, v48
	v_sub_f32_e32 v53, 1.0, v51
	v_sub_f32_e32 v56, 1.0, v54
	v_sub_f32_e32 v59, 1.0, v57
	v_add_f32_e32 v160, 1.0, v48
	v_add_f32_e32 v164, 1.0, v51
	v_add_f32_e32 v168, 1.0, v54
	v_add_f32_e32 v172, 1.0, v57
	v_mul_f32_e32 v50, v50, v160
	v_mul_f32_e32 v53, v53, v164
	v_mul_f32_e32 v56, v56, v168
	v_mul_f32_e32 v59, v59, v172
	v_max_f32_e32 v50, 0, v50
	v_max_f32_e32 v53, 0, v53
	v_max_f32_e32 v56, 0, v56
	v_max_f32_e32 v59, 0, v59
	v_sqrt_f32_e32 v50, v50
	v_sqrt_f32_e32 v53, v53
	v_sqrt_f32_e32 v56, v56
	v_sqrt_f32_e32 v59, v59
	v_mul_f32_e32 v49, v49, v50
	v_mul_f32_e32 v52, v52, v53
	v_mul_f32_e32 v55, v55, v56
	v_mul_f32_e32 v58, v58, v59
	v_fma_f32 v201, v201, v48, v49
	v_mov_b32_e32 v160, v201
	v_fma_f32 v201, v201, v51, v52
	v_mov_b32_e32 v164, v201
	v_fma_f32 v201, v201, v54, v55
	v_mov_b32_e32 v168, v201
	v_fma_f32 v201, v201, v57, v58
	v_mov_b32_e32 v172, v201
	s_waitcnt vmcnt(0)
	v_lshlrev_b32_e32 v48, 16, v176
	v_lshlrev_b32_e32 v51, 16, v180
	v_lshlrev_b32_e32 v54, 16, v184
	v_lshlrev_b32_e32 v57, 16, v188
	v_and_b32_e32 v49, 0xffff0000, v176
	v_and_b32_e32 v52, 0xffff0000, v180
	v_and_b32_e32 v55, 0xffff0000, v184
	v_and_b32_e32 v58, 0xffff0000, v188
	v_add_f32_e32 v48, v198, v48
	v_add_f32_e32 v51, v198, v51
	v_add_f32_e32 v54, v198, v54
	v_add_f32_e32 v57, v198, v57
	v_add_f32_e32 v49, v199, v49
	v_add_f32_e32 v52, v199, v52
	v_add_f32_e32 v55, v199, v55
	v_add_f32_e32 v58, v199, v58
	v_mul_f32_e32 v48, 0xbfb8aa3b, v48
	v_mul_f32_e32 v51, 0xbfb8aa3b, v51
	v_mul_f32_e32 v54, 0xbfb8aa3b, v54
	v_mul_f32_e32 v57, 0xbfb8aa3b, v57
	v_mul_f32_e32 v49, 0xbfb8aa3b, v49
	v_mul_f32_e32 v52, 0xbfb8aa3b, v52
	v_mul_f32_e32 v55, 0xbfb8aa3b, v55
	v_mul_f32_e32 v58, 0xbfb8aa3b, v58
	v_exp_f32_e32 v48, v48
	v_exp_f32_e32 v51, v51
	v_exp_f32_e32 v54, v54
	v_exp_f32_e32 v57, v57
	v_exp_f32_e32 v49, v49
	v_exp_f32_e32 v52, v52
	v_exp_f32_e32 v55, v55
	v_exp_f32_e32 v58, v58
	v_lshlrev_b32_e32 v50, 16, v178
	v_lshlrev_b32_e32 v53, 16, v182
	v_lshlrev_b32_e32 v56, 16, v186
	v_lshlrev_b32_e32 v59, 16, v190
	v_add_f32_e32 v48, 1.0, v48
	v_add_f32_e32 v51, 1.0, v51
	v_add_f32_e32 v54, 1.0, v54
	v_add_f32_e32 v57, 1.0, v57
	v_add_f32_e32 v49, 1.0, v49
	v_add_f32_e32 v52, 1.0, v52
	v_add_f32_e32 v55, 1.0, v55
	v_add_f32_e32 v58, 1.0, v58
	v_rcp_f32_e32 v48, v48
	v_rcp_f32_e32 v51, v51
	v_rcp_f32_e32 v54, v54
	v_rcp_f32_e32 v57, v57
	v_rcp_f32_e32 v49, v49
	v_rcp_f32_e32 v52, v52
	v_rcp_f32_e32 v55, v55
	v_rcp_f32_e32 v58, v58
	v_mul_f32_e32 v48, v200, v48
	v_mul_f32_e32 v51, v200, v51
	v_mul_f32_e32 v54, v200, v54
	v_mul_f32_e32 v57, v200, v57
	v_mul_f32_e32 v49, v49, v50
	v_mul_f32_e32 v52, v52, v53
	v_mul_f32_e32 v55, v55, v56
	v_mul_f32_e32 v58, v58, v59
	v_mul_f32_e32 v48, 0x3fb8aa3b, v48
	v_mul_f32_e32 v51, 0x3fb8aa3b, v51
	v_mul_f32_e32 v54, 0x3fb8aa3b, v54
	v_mul_f32_e32 v57, 0x3fb8aa3b, v57
	v_exp_f32_e32 v48, v48
	v_exp_f32_e32 v51, v51
	v_exp_f32_e32 v54, v54
	v_exp_f32_e32 v57, v57
	v_sub_f32_e32 v50, 1.0, v48
	v_sub_f32_e32 v53, 1.0, v51
	v_sub_f32_e32 v56, 1.0, v54
	v_sub_f32_e32 v59, 1.0, v57
	v_add_f32_e32 v176, 1.0, v48
	v_add_f32_e32 v180, 1.0, v51
	v_add_f32_e32 v184, 1.0, v54
	v_add_f32_e32 v188, 1.0, v57
	v_mul_f32_e32 v50, v50, v176
	v_mul_f32_e32 v53, v53, v180
	v_mul_f32_e32 v56, v56, v184
	v_mul_f32_e32 v59, v59, v188
	v_max_f32_e32 v50, 0, v50
	v_max_f32_e32 v53, 0, v53
	v_max_f32_e32 v56, 0, v56
	v_max_f32_e32 v59, 0, v59
	v_sqrt_f32_e32 v50, v50
	v_sqrt_f32_e32 v53, v53
	v_sqrt_f32_e32 v56, v56
	v_sqrt_f32_e32 v59, v59
	v_mul_f32_e32 v49, v49, v50
	v_mul_f32_e32 v52, v52, v53
	v_mul_f32_e32 v55, v55, v56
; __device__ __forceinline__ unsigned cvt_pk_bf16(float lo, float hi) { unsigned r; asm volatile("v_cvt_pk_bf16_f32 %0, %1, %2" : "=v"(r) : "v"(lo), "v"(hi)); return r; }
; __device__ __forceinline__ float fast_sigmoid(float x) { return __builtin_amdgcn_rcpf(1.f + __builtin_amdgcn_exp2f(-1.4426950408889634f * x)); }
; __device__ __forceinline__ float bf2f(unsigned short h) { return __uint_as_float(((unsigned)h) << 16); }
; __device__ __forceinline__ float bflo(unsigned w) { return __uint_as_float(w << 16); }
; __device__ __forceinline__ float bfhi(unsigned w) { return __uint_as_float(w & 0xffff0000u); }
; __device__ __forceinline__ float gelu_tanh(float x) { const float y = 0.7978845608028654f * (x + 0.044715f * x * x * x); const float t = 1.f - 2.f * __builtin_amdgcn_rcpf(1.f + __expf(2.f * y)); return 0.5f * x * (1.f + t); }
; __device__ __forceinline__ void scan_coef(float r, float i, float u, float sp8, float& a, float& b) { const float la = -sp8 * r; a = __expf(la); b = __builtin_amdgcn_sqrtf(fmaxf((1.f - a) * (1.f + a), 0.f)) * (i * u); }
; __global__ void __launch_bounds__(512) mega_fwd(Params P) {
;     ...
;                 for (int t = 0; t < 32; ++t) { const bf16_t* gp = XN + (size_t)(m0 + t) * 2048; const float u = bf2f(UC[(size_t)(m0 + t) * 512 + ch]);
;                     const unsigned g2 = *(const unsigned*)(gp + ch * 4);
;                     float a, b; scan_coef(pg8::fast_sigmoid(bflo(g2) + brf), pg8::fast_sigmoid(bfhi(g2) + bif), u, spf, a, b); hf = a * hf + b; hl[t * 512 + ch] = hf; }
;                 for (int tb = 28; tb >= 0; tb -= 4) { float rr[4], ii[4], uu[4], gg[4];
; #pragma unroll
;                     for (int k = 0; k < 4; ++k) { const bf16_t* gp = XN + (size_t)(m0 + tb + k) * 2048; { const unsigned g2 = *(const unsigned*)(gp + ch * 4 + 2); rr[k] = bflo(g2); ii[k] = bfhi(g2); }
;                         uu[k] = bf2f(UC[(size_t)(m0 + tb + k) * 512 + ch]); gg[k] = bf2f(GT[(size_t)(m0 + tb + k) * 512 + ch]); }
; #pragma unroll
;                     for (int k = 3; k >= 0; --k) { float a, b; scan_coef(pg8::fast_sigmoid(rr[k] + brb), pg8::fast_sigmoid(ii[k] + bib), uu[k], spb, a, b); hb = a * hb + b;
;                         const float y = gelu_tanh(gg[k]) * (hl[(tb + k) * 512 + ch] + hb); YC[(size_t)(m0 + tb + k) * 512 + ch] = (bf16_t)(cvt_pk_bf16(y, y) & 0xffff); } }
	v_mul_f32_e32 v58, v58, v59
	v_fma_f32 v201, v201, v48, v49
	v_mov_b32_e32 v176, v201
	v_fma_f32 v201, v201, v51, v52
	v_mov_b32_e32 v180, v201
	v_fma_f32 v201, v201, v54, v55
	v_mov_b32_e32 v184, v201
	v_fma_f32 v201, v201, v57, v58
	v_mov_b32_e32 v188, v201
	v_lshlrev_b32_e32 v48, 16, v189
	v_lshlrev_b32_e32 v51, 16, v185
	v_lshlrev_b32_e32 v54, 16, v181
	v_lshlrev_b32_e32 v57, 16, v177
	v_and_b32_e32 v49, 0xffff0000, v189
	v_and_b32_e32 v52, 0xffff0000, v185
	v_and_b32_e32 v55, 0xffff0000, v181
	v_and_b32_e32 v58, 0xffff0000, v177
	v_add_f32_e32 v48, v41, v48
	v_add_f32_e32 v51, v41, v51
	v_add_f32_e32 v54, v41, v54
	v_add_f32_e32 v57, v41, v57
	v_add_f32_e32 v49, v42, v49
	v_add_f32_e32 v52, v42, v52
	v_add_f32_e32 v55, v42, v55
	v_add_f32_e32 v58, v42, v58
	v_mul_f32_e32 v48, 0xbfb8aa3b, v48
	v_mul_f32_e32 v51, 0xbfb8aa3b, v51
	v_mul_f32_e32 v54, 0xbfb8aa3b, v54
	v_mul_f32_e32 v57, 0xbfb8aa3b, v57
	v_mul_f32_e32 v49, 0xbfb8aa3b, v49
	v_mul_f32_e32 v52, 0xbfb8aa3b, v52
	v_mul_f32_e32 v55, 0xbfb8aa3b, v55
	v_mul_f32_e32 v58, 0xbfb8aa3b, v58
	v_exp_f32_e32 v48, v48
	v_exp_f32_e32 v51, v51
	v_exp_f32_e32 v54, v54
	v_exp_f32_e32 v57, v57
	v_exp_f32_e32 v49, v49
	v_exp_f32_e32 v52, v52
	v_exp_f32_e32 v55, v55
	v_exp_f32_e32 v58, v58
	v_lshlrev_b32_e32 v50, 16, v190
	v_lshlrev_b32_e32 v53, 16, v186
	v_lshlrev_b32_e32 v56, 16, v182
	v_lshlrev_b32_e32 v59, 16, v178
	v_add_f32_e32 v48, 1.0, v48
	v_add_f32_e32 v51, 1.0, v51
	v_add_f32_e32 v54, 1.0, v54
	v_add_f32_e32 v57, 1.0, v57
	v_add_f32_e32 v49, 1.0, v49
	v_add_f32_e32 v52, 1.0, v52
	v_add_f32_e32 v55, 1.0, v55
	v_add_f32_e32 v58, 1.0, v58
	v_rcp_f32_e32 v48, v48
	v_rcp_f32_e32 v51, v51
	v_rcp_f32_e32 v54, v54
	v_rcp_f32_e32 v57, v57
	v_rcp_f32_e32 v49, v49
	v_rcp_f32_e32 v52, v52
	v_rcp_f32_e32 v55, v55
	v_rcp_f32_e32 v58, v58
	v_mul_f32_e32 v48, v43, v48
	v_mul_f32_e32 v51, v43, v51
	v_mul_f32_e32 v54, v43, v54
	v_mul_f32_e32 v57, v43, v57
	v_mul_f32_e32 v49, v49, v50
	v_mul_f32_e32 v52, v52, v53
	v_mul_f32_e32 v55, v55, v56
	v_mul_f32_e32 v58, v58, v59
	v_mul_f32_e32 v48, 0x3fb8aa3b, v48
	v_mul_f32_e32 v51, 0x3fb8aa3b, v51
	v_mul_f32_e32 v54, 0x3fb8aa3b, v54
	v_mul_f32_e32 v57, 0x3fb8aa3b, v57
	v_exp_f32_e32 v48, v48
	v_exp_f32_e32 v51, v51
	v_exp_f32_e32 v54, v54
	v_exp_f32_e32 v57, v57
	v_sub_f32_e32 v50, 1.0, v48
	v_sub_f32_e32 v53, 1.0, v51
	v_sub_f32_e32 v56, 1.0, v54
	v_sub_f32_e32 v59, 1.0, v57
	v_add_f32_e32 v189, 1.0, v48
	v_add_f32_e32 v185, 1.0, v51
	v_add_f32_e32 v181, 1.0, v54
	v_add_f32_e32 v177, 1.0, v57
	v_mul_f32_e32 v50, v50, v189
	v_mul_f32_e32 v53, v53, v185
	v_mul_f32_e32 v56, v56, v181
	v_mul_f32_e32 v59, v59, v177
	v_max_f32_e32 v50, 0, v50
	v_max_f32_e32 v53, 0, v53
	v_max_f32_e32 v56, 0, v56
	v_max_f32_e32 v59, 0, v59
	v_sqrt_f32_e32 v50, v50
	v_sqrt_f32_e32 v53, v53
	v_sqrt_f32_e32 v56, v56
	v_sqrt_f32_e32 v59, v59
	v_mul_f32_e32 v49, v49, v50
	v_mul_f32_e32 v52, v52, v53
	v_mul_f32_e32 v55, v55, v56
	v_mul_f32_e32 v58, v58, v59
	v_lshlrev_b32_e32 v191, 16, v191
	v_lshlrev_b32_e32 v187, 16, v187
	v_lshlrev_b32_e32 v183, 16, v183
	v_lshlrev_b32_e32 v179, 16, v179
	v_mul_f32_e32 v60, 0x3d372713, v191
	v_mul_f32_e32 v61, 0x3d372713, v187
	v_mul_f32_e32 v62, 0x3d372713, v183
	v_mul_f32_e32 v63, 0x3d372713, v179
	v_mul_f32_e32 v60, v60, v191
	v_mul_f32_e32 v61, v61, v187
	v_mul_f32_e32 v62, v62, v183
	v_mul_f32_e32 v63, v63, v179
	v_fma_f32 v60, v60, v191, v191
	v_fma_f32 v61, v61, v187, v187
	v_fma_f32 v62, v62, v183, v183
	v_fma_f32 v63, v63, v179, v179
	v_mul_f32_e32 v60, 0x3f4c422a, v60
	v_mul_f32_e32 v61, 0x3f4c422a, v61
	v_mul_f32_e32 v62, 0x3f4c422a, v62
	v_mul_f32_e32 v63, 0x3f4c422a, v63
	v_add_f32_e32 v60, v60, v60
	v_add_f32_e32 v61, v61, v61
	v_add_f32_e32 v62, v62, v62
	v_add_f32_e32 v63, v63, v63
	v_mul_f32_e32 v60, 0x3fb8aa3b, v60
	v_mul_f32_e32 v61, 0x3fb8aa3b, v61
	v_mul_f32_e32 v62, 0x3fb8aa3b, v62
	v_mul_f32_e32 v63, 0x3fb8aa3b, v63
	v_exp_f32_e32 v60, v60
	v_exp_f32_e32 v61, v61
	v_exp_f32_e32 v62, v62
	v_exp_f32_e32 v63, v63
	v_mul_f32_e32 v191, 0.5, v191
	v_mul_f32_e32 v187, 0.5, v187
	v_mul_f32_e32 v183, 0.5, v183
	v_mul_f32_e32 v179, 0.5, v179
	v_add_f32_e32 v60, 1.0, v60
	v_add_f32_e32 v61, 1.0, v61
	v_add_f32_e32 v62, 1.0, v62
	v_add_f32_e32 v63, 1.0, v63
	v_rcp_f32_e32 v60, v60
	v_rcp_f32_e32 v61, v61
	v_rcp_f32_e32 v62, v62
	v_rcp_f32_e32 v63, v63
	v_nop
	v_nop
	v_nop
	v_nop
	v_fma_f32 v60, v60, -2.0, 1.0
	v_fma_f32 v61, v61, -2.0, 1.0
	v_fma_f32 v62, v62, -2.0, 1.0
	v_fma_f32 v63, v63, -2.0, 1.0
	v_add_f32_e32 v60, 1.0, v60
	v_add_f32_e32 v61, 1.0, v61
	v_add_f32_e32 v62, 1.0, v62
	v_add_f32_e32 v63, 1.0, v63
	v_mul_f32_e32 v60, v191, v60
	v_mul_f32_e32 v61, v187, v61
	v_mul_f32_e32 v62, v183, v62
	v_mul_f32_e32 v63, v179, v63
	v_fma_f32 v32, v32, v48, v49
	v_add_f32_e32 v191, v188, v32
	v_mul_f32_e32 v60, v191, v60
	v_fma_f32 v32, v32, v51, v52
	v_add_f32_e32 v187, v184, v32
	v_mul_f32_e32 v61, v187, v61
	v_fma_f32 v32, v32, v54, v55
	v_add_f32_e32 v183, v180, v32
	v_mul_f32_e32 v62, v183, v62
	v_fma_f32 v32, v32, v57, v58
	v_add_f32_e32 v179, v176, v32
	v_mul_f32_e32 v63, v179, v63
	v_cvt_pk_bf16_f32 v60, v60, v60
	v_cvt_pk_bf16_f32 v61, v61, v61
	v_cvt_pk_bf16_f32 v62, v62, v62
	v_cvt_pk_bf16_f32 v63, v63, v63
	global_store_short v8, v60, s[56:57] offset:3072
	global_store_short v8, v61, s[56:57] offset:2048
	global_store_short v8, v62, s[56:57] offset:1024
	global_store_short v8, v63, s[56:57]
	s_sub_u32 s56, s56, 0x1000
	s_subb_u32 s57, s57, 0
	v_lshlrev_b32_e32 v48, 16, v173
	v_lshlrev_b32_e32 v51, 16, v169
	v_lshlrev_b32_e32 v54, 16, v165
	v_lshlrev_b32_e32 v57, 16, v161
	v_and_b32_e32 v49, 0xffff0000, v173
; __device__ __forceinline__ unsigned cvt_pk_bf16(float lo, float hi) { unsigned r; asm volatile("v_cvt_pk_bf16_f32 %0, %1, %2" : "=v"(r) : "v"(lo), "v"(hi)); return r; }
; __device__ __forceinline__ float fast_sigmoid(float x) { return __builtin_amdgcn_rcpf(1.f + __builtin_amdgcn_exp2f(-1.4426950408889634f * x)); }
; __device__ __forceinline__ float bf2f(unsigned short h) { return __uint_as_float(((unsigned)h) << 16); }
; __device__ __forceinline__ float bflo(unsigned w) { return __uint_as_float(w << 16); }
; __device__ __forceinline__ float bfhi(unsigned w) { return __uint_as_float(w & 0xffff0000u); }
; __device__ __forceinline__ float gelu_tanh(float x) { const float y = 0.7978845608028654f * (x + 0.044715f * x * x * x); const float t = 1.f - 2.f * __builtin_amdgcn_rcpf(1.f + __expf(2.f * y)); return 0.5f * x * (1.f + t); }
; __device__ __forceinline__ void scan_coef(float r, float i, float u, float sp8, float& a, float& b) { const float la = -sp8 * r; a = __expf(la); b = __builtin_amdgcn_sqrtf(fmaxf((1.f - a) * (1.f + a), 0.f)) * (i * u); }
; __global__ void __launch_bounds__(512) mega_fwd(Params P) {
;     ...
;                 for (int tb = 28; tb >= 0; tb -= 4) { float rr[4], ii[4], uu[4], gg[4];
; #pragma unroll
;                     for (int k = 0; k < 4; ++k) { const bf16_t* gp = XN + (size_t)(m0 + tb + k) * 2048; { const unsigned g2 = *(const unsigned*)(gp + ch * 4 + 2); rr[k] = bflo(g2); ii[k] = bfhi(g2); }
;                         uu[k] = bf2f(UC[(size_t)(m0 + tb + k) * 512 + ch]); gg[k] = bf2f(GT[(size_t)(m0 + tb + k) * 512 + ch]); }
; #pragma unroll
;                     for (int k = 3; k >= 0; --k) { float a, b; scan_coef(pg8::fast_sigmoid(rr[k] + brb), pg8::fast_sigmoid(ii[k] + bib), uu[k], spb, a, b); hb = a * hb + b;
;                         const float y = gelu_tanh(gg[k]) * (hl[(tb + k) * 512 + ch] + hb); YC[(size_t)(m0 + tb + k) * 512 + ch] = (bf16_t)(cvt_pk_bf16(y, y) & 0xffff); } }
	v_and_b32_e32 v52, 0xffff0000, v169
	v_and_b32_e32 v55, 0xffff0000, v165
	v_and_b32_e32 v58, 0xffff0000, v161
	v_add_f32_e32 v48, v41, v48
	v_add_f32_e32 v51, v41, v51
	v_add_f32_e32 v54, v41, v54
	v_add_f32_e32 v57, v41, v57
	v_add_f32_e32 v49, v42, v49
	v_add_f32_e32 v52, v42, v52
	v_add_f32_e32 v55, v42, v55
	v_add_f32_e32 v58, v42, v58
	v_mul_f32_e32 v48, 0xbfb8aa3b, v48
	v_mul_f32_e32 v51, 0xbfb8aa3b, v51
	v_mul_f32_e32 v54, 0xbfb8aa3b, v54
	v_mul_f32_e32 v57, 0xbfb8aa3b, v57
	v_mul_f32_e32 v49, 0xbfb8aa3b, v49
	v_mul_f32_e32 v52, 0xbfb8aa3b, v52
	v_mul_f32_e32 v55, 0xbfb8aa3b, v55
	v_mul_f32_e32 v58, 0xbfb8aa3b, v58
	v_exp_f32_e32 v48, v48
	v_exp_f32_e32 v51, v51
	v_exp_f32_e32 v54, v54
	v_exp_f32_e32 v57, v57
	v_exp_f32_e32 v49, v49
	v_exp_f32_e32 v52, v52
	v_exp_f32_e32 v55, v55
	v_exp_f32_e32 v58, v58
	v_lshlrev_b32_e32 v50, 16, v174
	v_lshlrev_b32_e32 v53, 16, v170
	v_lshlrev_b32_e32 v56, 16, v166
	v_lshlrev_b32_e32 v59, 16, v162
	v_add_f32_e32 v48, 1.0, v48
	v_add_f32_e32 v51, 1.0, v51
	v_add_f32_e32 v54, 1.0, v54
	v_add_f32_e32 v57, 1.0, v57
	v_add_f32_e32 v49, 1.0, v49
	v_add_f32_e32 v52, 1.0, v52
	v_add_f32_e32 v55, 1.0, v55
	v_add_f32_e32 v58, 1.0, v58
	v_rcp_f32_e32 v48, v48
	v_rcp_f32_e32 v51, v51
	v_rcp_f32_e32 v54, v54
	v_rcp_f32_e32 v57, v57
	v_rcp_f32_e32 v49, v49
	v_rcp_f32_e32 v52, v52
	v_rcp_f32_e32 v55, v55
	v_rcp_f32_e32 v58, v58
	v_mul_f32_e32 v48, v43, v48
	v_mul_f32_e32 v51, v43, v51
	v_mul_f32_e32 v54, v43, v54
	v_mul_f32_e32 v57, v43, v57
	v_mul_f32_e32 v49, v49, v50
	v_mul_f32_e32 v52, v52, v53
	v_mul_f32_e32 v55, v55, v56
	v_mul_f32_e32 v58, v58, v59
	v_mul_f32_e32 v48, 0x3fb8aa3b, v48
	v_mul_f32_e32 v51, 0x3fb8aa3b, v51
	v_mul_f32_e32 v54, 0x3fb8aa3b, v54
	v_mul_f32_e32 v57, 0x3fb8aa3b, v57
	v_exp_f32_e32 v48, v48
	v_exp_f32_e32 v51, v51
	v_exp_f32_e32 v54, v54
	v_exp_f32_e32 v57, v57
	v_sub_f32_e32 v50, 1.0, v48
	v_sub_f32_e32 v53, 1.0, v51
	v_sub_f32_e32 v56, 1.0, v54
	v_sub_f32_e32 v59, 1.0, v57
	v_add_f32_e32 v173, 1.0, v48
	v_add_f32_e32 v169, 1.0, v51
	v_add_f32_e32 v165, 1.0, v54
	v_add_f32_e32 v161, 1.0, v57
	v_mul_f32_e32 v50, v50, v173
	v_mul_f32_e32 v53, v53, v169
	v_mul_f32_e32 v56, v56, v165
	v_mul_f32_e32 v59, v59, v161
	v_max_f32_e32 v50, 0, v50
	v_max_f32_e32 v53, 0, v53
	v_max_f32_e32 v56, 0, v56
	v_max_f32_e32 v59, 0, v59
	v_sqrt_f32_e32 v50, v50
	v_sqrt_f32_e32 v53, v53
	v_sqrt_f32_e32 v56, v56
	v_sqrt_f32_e32 v59, v59
	v_mul_f32_e32 v49, v49, v50
	v_mul_f32_e32 v52, v52, v53
	v_mul_f32_e32 v55, v55, v56
	v_mul_f32_e32 v58, v58, v59
	v_lshlrev_b32_e32 v175, 16, v175
	v_lshlrev_b32_e32 v171, 16, v171
	v_lshlrev_b32_e32 v167, 16, v167
	v_lshlrev_b32_e32 v163, 16, v163
	v_mul_f32_e32 v60, 0x3d372713, v175
	v_mul_f32_e32 v61, 0x3d372713, v171
	v_mul_f32_e32 v62, 0x3d372713, v167
	v_mul_f32_e32 v63, 0x3d372713, v163
	v_mul_f32_e32 v60, v60, v175
	v_mul_f32_e32 v61, v61, v171
	v_mul_f32_e32 v62, v62, v167
	v_mul_f32_e32 v63, v63, v163
	v_fma_f32 v60, v60, v175, v175
	v_fma_f32 v61, v61, v171, v171
	v_fma_f32 v62, v62, v167, v167
	v_fma_f32 v63, v63, v163, v163
	v_mul_f32_e32 v60, 0x3f4c422a, v60
	v_mul_f32_e32 v61, 0x3f4c422a, v61
	v_mul_f32_e32 v62, 0x3f4c422a, v62
	v_mul_f32_e32 v63, 0x3f4c422a, v63
	v_add_f32_e32 v60, v60, v60
	v_add_f32_e32 v61, v61, v61
	v_add_f32_e32 v62, v62, v62
	v_add_f32_e32 v63, v63, v63
	v_mul_f32_e32 v60, 0x3fb8aa3b, v60
	v_mul_f32_e32 v61, 0x3fb8aa3b, v61
	v_mul_f32_e32 v62, 0x3fb8aa3b, v62
	v_mul_f32_e32 v63, 0x3fb8aa3b, v63
	v_exp_f32_e32 v60, v60
	v_exp_f32_e32 v61, v61
	v_exp_f32_e32 v62, v62
	v_exp_f32_e32 v63, v63
	v_mul_f32_e32 v175, 0.5, v175
	v_mul_f32_e32 v171, 0.5, v171
	v_mul_f32_e32 v167, 0.5, v167
	v_mul_f32_e32 v163, 0.5, v163
	v_add_f32_e32 v60, 1.0, v60
	v_add_f32_e32 v61, 1.0, v61
	v_add_f32_e32 v62, 1.0, v62
	v_add_f32_e32 v63, 1.0, v63
	v_rcp_f32_e32 v60, v60
	v_rcp_f32_e32 v61, v61
	v_rcp_f32_e32 v62, v62
	v_rcp_f32_e32 v63, v63
	v_nop
	v_nop
	v_nop
	v_nop
	v_fma_f32 v60, v60, -2.0, 1.0
	v_fma_f32 v61, v61, -2.0, 1.0
	v_fma_f32 v62, v62, -2.0, 1.0
	v_fma_f32 v63, v63, -2.0, 1.0
	v_add_f32_e32 v60, 1.0, v60
	v_add_f32_e32 v61, 1.0, v61
	v_add_f32_e32 v62, 1.0, v62
	v_add_f32_e32 v63, 1.0, v63
	v_mul_f32_e32 v60, v175, v60
	v_mul_f32_e32 v61, v171, v61
	v_mul_f32_e32 v62, v167, v62
	v_mul_f32_e32 v63, v163, v63
	v_fma_f32 v32, v32, v48, v49
	v_add_f32_e32 v175, v172, v32
	v_mul_f32_e32 v60, v175, v60
	v_fma_f32 v32, v32, v51, v52
	v_add_f32_e32 v171, v168, v32
	v_mul_f32_e32 v61, v171, v61
	v_fma_f32 v32, v32, v54, v55
	v_add_f32_e32 v167, v164, v32
	v_mul_f32_e32 v62, v167, v62
	v_fma_f32 v32, v32, v57, v58
	v_add_f32_e32 v163, v160, v32
	v_mul_f32_e32 v63, v163, v63
	v_cvt_pk_bf16_f32 v60, v60, v60
	v_cvt_pk_bf16_f32 v61, v61, v61
	v_cvt_pk_bf16_f32 v62, v62, v62
	v_cvt_pk_bf16_f32 v63, v63, v63
	global_store_short v8, v60, s[56:57] offset:3072
	global_store_short v8, v61, s[56:57] offset:2048
	global_store_short v8, v62, s[56:57] offset:1024
	global_store_short v8, v63, s[56:57]
	s_sub_u32 s56, s56, 0x1000
	s_subb_u32 s57, s57, 0
	v_lshlrev_b32_e32 v48, 16, v157
	v_lshlrev_b32_e32 v51, 16, v153
	v_lshlrev_b32_e32 v54, 16, v149
	v_lshlrev_b32_e32 v57, 16, v145
	v_and_b32_e32 v49, 0xffff0000, v157
	v_and_b32_e32 v52, 0xffff0000, v153
	v_and_b32_e32 v55, 0xffff0000, v149
	v_and_b32_e32 v58, 0xffff0000, v145
	v_add_f32_e32 v48, v41, v48
	v_add_f32_e32 v51, v41, v51
	v_add_f32_e32 v54, v41, v54
	v_add_f32_e32 v57, v41, v57
	v_add_f32_e32 v49, v42, v49
	v_add_f32_e32 v52, v42, v52
	v_add_f32_e32 v55, v42, v55
	v_add_f32_e32 v58, v42, v58
	v_mul_f32_e32 v48, 0xbfb8aa3b, v48
	v_mul_f32_e32 v51, 0xbfb8aa3b, v51
	v_mul_f32_e32 v54, 0xbfb8aa3b, v54
; __device__ __forceinline__ unsigned cvt_pk_bf16(float lo, float hi) { unsigned r; asm volatile("v_cvt_pk_bf16_f32 %0, %1, %2" : "=v"(r) : "v"(lo), "v"(hi)); return r; }
; __device__ __forceinline__ float fast_sigmoid(float x) { return __builtin_amdgcn_rcpf(1.f + __builtin_amdgcn_exp2f(-1.4426950408889634f * x)); }
; __device__ __forceinline__ float bf2f(unsigned short h) { return __uint_as_float(((unsigned)h) << 16); }
; __device__ __forceinline__ float bflo(unsigned w) { return __uint_as_float(w << 16); }
; __device__ __forceinline__ float bfhi(unsigned w) { return __uint_as_float(w & 0xffff0000u); }
; __device__ __forceinline__ float gelu_tanh(float x) { const float y = 0.7978845608028654f * (x + 0.044715f * x * x * x); const float t = 1.f - 2.f * __builtin_amdgcn_rcpf(1.f + __expf(2.f * y)); return 0.5f * x * (1.f + t); }
; __device__ __forceinline__ void scan_coef(float r, float i, float u, float sp8, float& a, float& b) { const float la = -sp8 * r; a = __expf(la); b = __builtin_amdgcn_sqrtf(fmaxf((1.f - a) * (1.f + a), 0.f)) * (i * u); }
; __global__ void __launch_bounds__(512) mega_fwd(Params P) {
;     ...
;                 for (int tb = 28; tb >= 0; tb -= 4) { float rr[4], ii[4], uu[4], gg[4];
; #pragma unroll
;                     for (int k = 0; k < 4; ++k) { const bf16_t* gp = XN + (size_t)(m0 + tb + k) * 2048; { const unsigned g2 = *(const unsigned*)(gp + ch * 4 + 2); rr[k] = bflo(g2); ii[k] = bfhi(g2); }
;                         uu[k] = bf2f(UC[(size_t)(m0 + tb + k) * 512 + ch]); gg[k] = bf2f(GT[(size_t)(m0 + tb + k) * 512 + ch]); }
; #pragma unroll
;                     for (int k = 3; k >= 0; --k) { float a, b; scan_coef(pg8::fast_sigmoid(rr[k] + brb), pg8::fast_sigmoid(ii[k] + bib), uu[k], spb, a, b); hb = a * hb + b;
;                         const float y = gelu_tanh(gg[k]) * (hl[(tb + k) * 512 + ch] + hb); YC[(size_t)(m0 + tb + k) * 512 + ch] = (bf16_t)(cvt_pk_bf16(y, y) & 0xffff); } }
	v_mul_f32_e32 v57, 0xbfb8aa3b, v57
	v_mul_f32_e32 v49, 0xbfb8aa3b, v49
	v_mul_f32_e32 v52, 0xbfb8aa3b, v52
	v_mul_f32_e32 v55, 0xbfb8aa3b, v55
	v_mul_f32_e32 v58, 0xbfb8aa3b, v58
	v_exp_f32_e32 v48, v48
	v_exp_f32_e32 v51, v51
	v_exp_f32_e32 v54, v54
	v_exp_f32_e32 v57, v57
	v_exp_f32_e32 v49, v49
	v_exp_f32_e32 v52, v52
	v_exp_f32_e32 v55, v55
	v_exp_f32_e32 v58, v58
	v_lshlrev_b32_e32 v50, 16, v158
	v_lshlrev_b32_e32 v53, 16, v154
	v_lshlrev_b32_e32 v56, 16, v150
	v_lshlrev_b32_e32 v59, 16, v146
	v_add_f32_e32 v48, 1.0, v48
	v_add_f32_e32 v51, 1.0, v51
	v_add_f32_e32 v54, 1.0, v54
	v_add_f32_e32 v57, 1.0, v57
	v_add_f32_e32 v49, 1.0, v49
	v_add_f32_e32 v52, 1.0, v52
	v_add_f32_e32 v55, 1.0, v55
	v_add_f32_e32 v58, 1.0, v58
	v_rcp_f32_e32 v48, v48
	v_rcp_f32_e32 v51, v51
	v_rcp_f32_e32 v54, v54
	v_rcp_f32_e32 v57, v57
	v_rcp_f32_e32 v49, v49
	v_rcp_f32_e32 v52, v52
	v_rcp_f32_e32 v55, v55
	v_rcp_f32_e32 v58, v58
	v_mul_f32_e32 v48, v43, v48
	v_mul_f32_e32 v51, v43, v51
	v_mul_f32_e32 v54, v43, v54
	v_mul_f32_e32 v57, v43, v57
	v_mul_f32_e32 v49, v49, v50
	v_mul_f32_e32 v52, v52, v53
	v_mul_f32_e32 v55, v55, v56
	v_mul_f32_e32 v58, v58, v59
	v_mul_f32_e32 v48, 0x3fb8aa3b, v48
	v_mul_f32_e32 v51, 0x3fb8aa3b, v51
	v_mul_f32_e32 v54, 0x3fb8aa3b, v54
	v_mul_f32_e32 v57, 0x3fb8aa3b, v57
	v_exp_f32_e32 v48, v48
	v_exp_f32_e32 v51, v51
	v_exp_f32_e32 v54, v54
	v_exp_f32_e32 v57, v57
	v_sub_f32_e32 v50, 1.0, v48
	v_sub_f32_e32 v53, 1.0, v51
	v_sub_f32_e32 v56, 1.0, v54
	v_sub_f32_e32 v59, 1.0, v57
	v_add_f32_e32 v157, 1.0, v48
	v_add_f32_e32 v153, 1.0, v51
	v_add_f32_e32 v149, 1.0, v54
	v_add_f32_e32 v145, 1.0, v57
	v_mul_f32_e32 v50, v50, v157
	v_mul_f32_e32 v53, v53, v153
	v_mul_f32_e32 v56, v56, v149
	v_mul_f32_e32 v59, v59, v145
	v_max_f32_e32 v50, 0, v50
	v_max_f32_e32 v53, 0, v53
	v_max_f32_e32 v56, 0, v56
	v_max_f32_e32 v59, 0, v59
	v_sqrt_f32_e32 v50, v50
	v_sqrt_f32_e32 v53, v53
	v_sqrt_f32_e32 v56, v56
	v_sqrt_f32_e32 v59, v59
	v_mul_f32_e32 v49, v49, v50
	v_mul_f32_e32 v52, v52, v53
	v_mul_f32_e32 v55, v55, v56
	v_mul_f32_e32 v58, v58, v59
	v_lshlrev_b32_e32 v159, 16, v159
	v_lshlrev_b32_e32 v155, 16, v155
	v_lshlrev_b32_e32 v151, 16, v151
	v_lshlrev_b32_e32 v147, 16, v147
	v_mul_f32_e32 v60, 0x3d372713, v159
	v_mul_f32_e32 v61, 0x3d372713, v155
	v_mul_f32_e32 v62, 0x3d372713, v151
	v_mul_f32_e32 v63, 0x3d372713, v147
	v_mul_f32_e32 v60, v60, v159
	v_mul_f32_e32 v61, v61, v155
	v_mul_f32_e32 v62, v62, v151
	v_mul_f32_e32 v63, v63, v147
	v_fma_f32 v60, v60, v159, v159
	v_fma_f32 v61, v61, v155, v155
	v_fma_f32 v62, v62, v151, v151
	v_fma_f32 v63, v63, v147, v147
	v_mul_f32_e32 v60, 0x3f4c422a, v60
	v_mul_f32_e32 v61, 0x3f4c422a, v61
	v_mul_f32_e32 v62, 0x3f4c422a, v62
	v_mul_f32_e32 v63, 0x3f4c422a, v63
	v_add_f32_e32 v60, v60, v60
	v_add_f32_e32 v61, v61, v61
	v_add_f32_e32 v62, v62, v62
	v_add_f32_e32 v63, v63, v63
	v_mul_f32_e32 v60, 0x3fb8aa3b, v60
	v_mul_f32_e32 v61, 0x3fb8aa3b, v61
	v_mul_f32_e32 v62, 0x3fb8aa3b, v62
	v_mul_f32_e32 v63, 0x3fb8aa3b, v63
	v_exp_f32_e32 v60, v60
	v_exp_f32_e32 v61, v61
	v_exp_f32_e32 v62, v62
	v_exp_f32_e32 v63, v63
	v_mul_f32_e32 v159, 0.5, v159
	v_mul_f32_e32 v155, 0.5, v155
	v_mul_f32_e32 v151, 0.5, v151
	v_mul_f32_e32 v147, 0.5, v147
	v_add_f32_e32 v60, 1.0, v60
	v_add_f32_e32 v61, 1.0, v61
	v_add_f32_e32 v62, 1.0, v62
	v_add_f32_e32 v63, 1.0, v63
	v_rcp_f32_e32 v60, v60
	v_rcp_f32_e32 v61, v61
	v_rcp_f32_e32 v62, v62
	v_rcp_f32_e32 v63, v63
	v_nop
	v_nop
	v_nop
	v_nop
	v_fma_f32 v60, v60, -2.0, 1.0
	v_fma_f32 v61, v61, -2.0, 1.0
	v_fma_f32 v62, v62, -2.0, 1.0
	v_fma_f32 v63, v63, -2.0, 1.0
	v_add_f32_e32 v60, 1.0, v60
	v_add_f32_e32 v61, 1.0, v61
	v_add_f32_e32 v62, 1.0, v62
	v_add_f32_e32 v63, 1.0, v63
	v_mul_f32_e32 v60, v159, v60
	v_mul_f32_e32 v61, v155, v61
	v_mul_f32_e32 v62, v151, v62
	v_mul_f32_e32 v63, v147, v63
	v_fma_f32 v32, v32, v48, v49
	v_add_f32_e32 v159, v156, v32
	v_mul_f32_e32 v60, v159, v60
	v_fma_f32 v32, v32, v51, v52
	v_add_f32_e32 v155, v152, v32
	v_mul_f32_e32 v61, v155, v61
	v_fma_f32 v32, v32, v54, v55
	v_add_f32_e32 v151, v148, v32
	v_mul_f32_e32 v62, v151, v62
	v_fma_f32 v32, v32, v57, v58
	v_add_f32_e32 v147, v144, v32
	v_mul_f32_e32 v63, v147, v63
	v_cvt_pk_bf16_f32 v60, v60, v60
	v_cvt_pk_bf16_f32 v61, v61, v61
	v_cvt_pk_bf16_f32 v62, v62, v62
	v_cvt_pk_bf16_f32 v63, v63, v63
	global_store_short v8, v60, s[56:57] offset:3072
	global_store_short v8, v61, s[56:57] offset:2048
	global_store_short v8, v62, s[56:57] offset:1024
	global_store_short v8, v63, s[56:57]
	s_sub_u32 s56, s56, 0x1000
	s_subb_u32 s57, s57, 0
	v_lshlrev_b32_e32 v48, 16, v141
	v_lshlrev_b32_e32 v51, 16, v137
	v_lshlrev_b32_e32 v54, 16, v133
	v_lshlrev_b32_e32 v57, 16, v129
	v_and_b32_e32 v49, 0xffff0000, v141
	v_and_b32_e32 v52, 0xffff0000, v137
	v_and_b32_e32 v55, 0xffff0000, v133
	v_and_b32_e32 v58, 0xffff0000, v129
	v_add_f32_e32 v48, v41, v48
	v_add_f32_e32 v51, v41, v51
	v_add_f32_e32 v54, v41, v54
	v_add_f32_e32 v57, v41, v57
	v_add_f32_e32 v49, v42, v49
	v_add_f32_e32 v52, v42, v52
	v_add_f32_e32 v55, v42, v55
	v_add_f32_e32 v58, v42, v58
	v_mul_f32_e32 v48, 0xbfb8aa3b, v48
	v_mul_f32_e32 v51, 0xbfb8aa3b, v51
	v_mul_f32_e32 v54, 0xbfb8aa3b, v54
	v_mul_f32_e32 v57, 0xbfb8aa3b, v57
	v_mul_f32_e32 v49, 0xbfb8aa3b, v49
	v_mul_f32_e32 v52, 0xbfb8aa3b, v52
	v_mul_f32_e32 v55, 0xbfb8aa3b, v55
	v_mul_f32_e32 v58, 0xbfb8aa3b, v58
	v_exp_f32_e32 v48, v48
	v_exp_f32_e32 v51, v51
	v_exp_f32_e32 v54, v54
	v_exp_f32_e32 v57, v57
	v_exp_f32_e32 v49, v49
	v_exp_f32_e32 v52, v52
	v_exp_f32_e32 v55, v55
	v_exp_f32_e32 v58, v58
	v_lshlrev_b32_e32 v50, 16, v142
	v_lshlrev_b32_e32 v53, 16, v138
; __device__ __forceinline__ unsigned cvt_pk_bf16(float lo, float hi) { unsigned r; asm volatile("v_cvt_pk_bf16_f32 %0, %1, %2" : "=v"(r) : "v"(lo), "v"(hi)); return r; }
; __device__ __forceinline__ float fast_sigmoid(float x) { return __builtin_amdgcn_rcpf(1.f + __builtin_amdgcn_exp2f(-1.4426950408889634f * x)); }
; __device__ __forceinline__ float bf2f(unsigned short h) { return __uint_as_float(((unsigned)h) << 16); }
; __device__ __forceinline__ float bflo(unsigned w) { return __uint_as_float(w << 16); }
; __device__ __forceinline__ float bfhi(unsigned w) { return __uint_as_float(w & 0xffff0000u); }
; __device__ __forceinline__ float gelu_tanh(float x) { const float y = 0.7978845608028654f * (x + 0.044715f * x * x * x); const float t = 1.f - 2.f * __builtin_amdgcn_rcpf(1.f + __expf(2.f * y)); return 0.5f * x * (1.f + t); }
; __device__ __forceinline__ void scan_coef(float r, float i, float u, float sp8, float& a, float& b) { const float la = -sp8 * r; a = __expf(la); b = __builtin_amdgcn_sqrtf(fmaxf((1.f - a) * (1.f + a), 0.f)) * (i * u); }
; __global__ void __launch_bounds__(512) mega_fwd(Params P) {
;     ...
;                 for (int tb = 28; tb >= 0; tb -= 4) { float rr[4], ii[4], uu[4], gg[4];
; #pragma unroll
;                     for (int k = 0; k < 4; ++k) { const bf16_t* gp = XN + (size_t)(m0 + tb + k) * 2048; { const unsigned g2 = *(const unsigned*)(gp + ch * 4 + 2); rr[k] = bflo(g2); ii[k] = bfhi(g2); }
;                         uu[k] = bf2f(UC[(size_t)(m0 + tb + k) * 512 + ch]); gg[k] = bf2f(GT[(size_t)(m0 + tb + k) * 512 + ch]); }
; #pragma unroll
;                     for (int k = 3; k >= 0; --k) { float a, b; scan_coef(pg8::fast_sigmoid(rr[k] + brb), pg8::fast_sigmoid(ii[k] + bib), uu[k], spb, a, b); hb = a * hb + b;
;                         const float y = gelu_tanh(gg[k]) * (hl[(tb + k) * 512 + ch] + hb); YC[(size_t)(m0 + tb + k) * 512 + ch] = (bf16_t)(cvt_pk_bf16(y, y) & 0xffff); } }
	v_lshlrev_b32_e32 v56, 16, v134
	v_lshlrev_b32_e32 v59, 16, v130
	v_add_f32_e32 v48, 1.0, v48
	v_add_f32_e32 v51, 1.0, v51
	v_add_f32_e32 v54, 1.0, v54
	v_add_f32_e32 v57, 1.0, v57
	v_add_f32_e32 v49, 1.0, v49
	v_add_f32_e32 v52, 1.0, v52
	v_add_f32_e32 v55, 1.0, v55
	v_add_f32_e32 v58, 1.0, v58
	v_rcp_f32_e32 v48, v48
	v_rcp_f32_e32 v51, v51
	v_rcp_f32_e32 v54, v54
	v_rcp_f32_e32 v57, v57
	v_rcp_f32_e32 v49, v49
	v_rcp_f32_e32 v52, v52
	v_rcp_f32_e32 v55, v55
	v_rcp_f32_e32 v58, v58
	v_mul_f32_e32 v48, v43, v48
	v_mul_f32_e32 v51, v43, v51
	v_mul_f32_e32 v54, v43, v54
	v_mul_f32_e32 v57, v43, v57
	v_mul_f32_e32 v49, v49, v50
	v_mul_f32_e32 v52, v52, v53
	v_mul_f32_e32 v55, v55, v56
	v_mul_f32_e32 v58, v58, v59
	v_mul_f32_e32 v48, 0x3fb8aa3b, v48
	v_mul_f32_e32 v51, 0x3fb8aa3b, v51
	v_mul_f32_e32 v54, 0x3fb8aa3b, v54
	v_mul_f32_e32 v57, 0x3fb8aa3b, v57
	v_exp_f32_e32 v48, v48
	v_exp_f32_e32 v51, v51
	v_exp_f32_e32 v54, v54
	v_exp_f32_e32 v57, v57
	v_sub_f32_e32 v50, 1.0, v48
	v_sub_f32_e32 v53, 1.0, v51
	v_sub_f32_e32 v56, 1.0, v54
	v_sub_f32_e32 v59, 1.0, v57
	v_add_f32_e32 v141, 1.0, v48
	v_add_f32_e32 v137, 1.0, v51
	v_add_f32_e32 v133, 1.0, v54
	v_add_f32_e32 v129, 1.0, v57
	v_mul_f32_e32 v50, v50, v141
	v_mul_f32_e32 v53, v53, v137
	v_mul_f32_e32 v56, v56, v133
	v_mul_f32_e32 v59, v59, v129
	v_max_f32_e32 v50, 0, v50
	v_max_f32_e32 v53, 0, v53
	v_max_f32_e32 v56, 0, v56
	v_max_f32_e32 v59, 0, v59
	v_sqrt_f32_e32 v50, v50
	v_sqrt_f32_e32 v53, v53
	v_sqrt_f32_e32 v56, v56
	v_sqrt_f32_e32 v59, v59
	v_mul_f32_e32 v49, v49, v50
	v_mul_f32_e32 v52, v52, v53
	v_mul_f32_e32 v55, v55, v56
	v_mul_f32_e32 v58, v58, v59
	v_lshlrev_b32_e32 v143, 16, v143
	v_lshlrev_b32_e32 v139, 16, v139
	v_lshlrev_b32_e32 v135, 16, v135
	v_lshlrev_b32_e32 v131, 16, v131
	v_mul_f32_e32 v60, 0x3d372713, v143
	v_mul_f32_e32 v61, 0x3d372713, v139
	v_mul_f32_e32 v62, 0x3d372713, v135
	v_mul_f32_e32 v63, 0x3d372713, v131
	v_mul_f32_e32 v60, v60, v143
	v_mul_f32_e32 v61, v61, v139
	v_mul_f32_e32 v62, v62, v135
	v_mul_f32_e32 v63, v63, v131
	v_fma_f32 v60, v60, v143, v143
	v_fma_f32 v61, v61, v139, v139
	v_fma_f32 v62, v62, v135, v135
	v_fma_f32 v63, v63, v131, v131
	v_mul_f32_e32 v60, 0x3f4c422a, v60
	v_mul_f32_e32 v61, 0x3f4c422a, v61
	v_mul_f32_e32 v62, 0x3f4c422a, v62
	v_mul_f32_e32 v63, 0x3f4c422a, v63
	v_add_f32_e32 v60, v60, v60
	v_add_f32_e32 v61, v61, v61
	v_add_f32_e32 v62, v62, v62
	v_add_f32_e32 v63, v63, v63
	v_mul_f32_e32 v60, 0x3fb8aa3b, v60
	v_mul_f32_e32 v61, 0x3fb8aa3b, v61
	v_mul_f32_e32 v62, 0x3fb8aa3b, v62
	v_mul_f32_e32 v63, 0x3fb8aa3b, v63
	v_exp_f32_e32 v60, v60
	v_exp_f32_e32 v61, v61
	v_exp_f32_e32 v62, v62
	v_exp_f32_e32 v63, v63
	v_mul_f32_e32 v143, 0.5, v143
	v_mul_f32_e32 v139, 0.5, v139
	v_mul_f32_e32 v135, 0.5, v135
	v_mul_f32_e32 v131, 0.5, v131
	v_add_f32_e32 v60, 1.0, v60
	v_add_f32_e32 v61, 1.0, v61
	v_add_f32_e32 v62, 1.0, v62
	v_add_f32_e32 v63, 1.0, v63
	v_rcp_f32_e32 v60, v60
	v_rcp_f32_e32 v61, v61
	v_rcp_f32_e32 v62, v62
	v_rcp_f32_e32 v63, v63
	v_nop
	v_nop
	v_nop
	v_nop
	v_fma_f32 v60, v60, -2.0, 1.0
	v_fma_f32 v61, v61, -2.0, 1.0
	v_fma_f32 v62, v62, -2.0, 1.0
	v_fma_f32 v63, v63, -2.0, 1.0
	v_add_f32_e32 v60, 1.0, v60
	v_add_f32_e32 v61, 1.0, v61
	v_add_f32_e32 v62, 1.0, v62
	v_add_f32_e32 v63, 1.0, v63
	v_mul_f32_e32 v60, v143, v60
	v_mul_f32_e32 v61, v139, v61
	v_mul_f32_e32 v62, v135, v62
	v_mul_f32_e32 v63, v131, v63
	v_fma_f32 v32, v32, v48, v49
	v_add_f32_e32 v143, v140, v32
	v_mul_f32_e32 v60, v143, v60
	v_fma_f32 v32, v32, v51, v52
	v_add_f32_e32 v139, v136, v32
	v_mul_f32_e32 v61, v139, v61
	v_fma_f32 v32, v32, v54, v55
	v_add_f32_e32 v135, v132, v32
	v_mul_f32_e32 v62, v135, v62
	v_fma_f32 v32, v32, v57, v58
	v_add_f32_e32 v131, v128, v32
	v_mul_f32_e32 v63, v131, v63
	v_cvt_pk_bf16_f32 v60, v60, v60
	v_cvt_pk_bf16_f32 v61, v61, v61
	v_cvt_pk_bf16_f32 v62, v62, v62
	v_cvt_pk_bf16_f32 v63, v63, v63
	global_store_short v8, v60, s[56:57] offset:3072
	global_store_short v8, v61, s[56:57] offset:2048
	global_store_short v8, v62, s[56:57] offset:1024
	global_store_short v8, v63, s[56:57]
	s_sub_u32 s56, s56, 0x1000
	s_subb_u32 s57, s57, 0
	v_lshlrev_b32_e32 v48, 16, v125
	v_lshlrev_b32_e32 v51, 16, v121
	v_lshlrev_b32_e32 v54, 16, v117
	v_lshlrev_b32_e32 v57, 16, v113
	v_and_b32_e32 v49, 0xffff0000, v125
	v_and_b32_e32 v52, 0xffff0000, v121
	v_and_b32_e32 v55, 0xffff0000, v117
	v_and_b32_e32 v58, 0xffff0000, v113
	v_add_f32_e32 v48, v41, v48
	v_add_f32_e32 v51, v41, v51
	v_add_f32_e32 v54, v41, v54
	v_add_f32_e32 v57, v41, v57
	v_add_f32_e32 v49, v42, v49
	v_add_f32_e32 v52, v42, v52
	v_add_f32_e32 v55, v42, v55
	v_add_f32_e32 v58, v42, v58
	v_mul_f32_e32 v48, 0xbfb8aa3b, v48
	v_mul_f32_e32 v51, 0xbfb8aa3b, v51
	v_mul_f32_e32 v54, 0xbfb8aa3b, v54
	v_mul_f32_e32 v57, 0xbfb8aa3b, v57
	v_mul_f32_e32 v49, 0xbfb8aa3b, v49
	v_mul_f32_e32 v52, 0xbfb8aa3b, v52
	v_mul_f32_e32 v55, 0xbfb8aa3b, v55
	v_mul_f32_e32 v58, 0xbfb8aa3b, v58
	v_exp_f32_e32 v48, v48
	v_exp_f32_e32 v51, v51
	v_exp_f32_e32 v54, v54
	v_exp_f32_e32 v57, v57
	v_exp_f32_e32 v49, v49
	v_exp_f32_e32 v52, v52
	v_exp_f32_e32 v55, v55
	v_exp_f32_e32 v58, v58
	v_lshlrev_b32_e32 v50, 16, v126
	v_lshlrev_b32_e32 v53, 16, v122
	v_lshlrev_b32_e32 v56, 16, v118
	v_lshlrev_b32_e32 v59, 16, v114
	v_add_f32_e32 v48, 1.0, v48
	v_add_f32_e32 v51, 1.0, v51
	v_add_f32_e32 v54, 1.0, v54
	v_add_f32_e32 v57, 1.0, v57
	v_add_f32_e32 v49, 1.0, v49
	v_add_f32_e32 v52, 1.0, v52
	v_add_f32_e32 v55, 1.0, v55
	v_add_f32_e32 v58, 1.0, v58
	v_rcp_f32_e32 v48, v48
	v_rcp_f32_e32 v51, v51
	v_rcp_f32_e32 v54, v54
	v_rcp_f32_e32 v57, v57
	v_rcp_f32_e32 v49, v49
	v_rcp_f32_e32 v52, v52
; __device__ __forceinline__ unsigned cvt_pk_bf16(float lo, float hi) { unsigned r; asm volatile("v_cvt_pk_bf16_f32 %0, %1, %2" : "=v"(r) : "v"(lo), "v"(hi)); return r; }
; __device__ __forceinline__ float fast_sigmoid(float x) { return __builtin_amdgcn_rcpf(1.f + __builtin_amdgcn_exp2f(-1.4426950408889634f * x)); }
; __device__ __forceinline__ float bf2f(unsigned short h) { return __uint_as_float(((unsigned)h) << 16); }
; __device__ __forceinline__ float bflo(unsigned w) { return __uint_as_float(w << 16); }
; __device__ __forceinline__ float bfhi(unsigned w) { return __uint_as_float(w & 0xffff0000u); }
; __device__ __forceinline__ float gelu_tanh(float x) { const float y = 0.7978845608028654f * (x + 0.044715f * x * x * x); const float t = 1.f - 2.f * __builtin_amdgcn_rcpf(1.f + __expf(2.f * y)); return 0.5f * x * (1.f + t); }
; __device__ __forceinline__ void scan_coef(float r, float i, float u, float sp8, float& a, float& b) { const float la = -sp8 * r; a = __expf(la); b = __builtin_amdgcn_sqrtf(fmaxf((1.f - a) * (1.f + a), 0.f)) * (i * u); }
; __global__ void __launch_bounds__(512) mega_fwd(Params P) {
;     ...
;                 for (int tb = 28; tb >= 0; tb -= 4) { float rr[4], ii[4], uu[4], gg[4];
; #pragma unroll
;                     for (int k = 0; k < 4; ++k) { const bf16_t* gp = XN + (size_t)(m0 + tb + k) * 2048; { const unsigned g2 = *(const unsigned*)(gp + ch * 4 + 2); rr[k] = bflo(g2); ii[k] = bfhi(g2); }
;                         uu[k] = bf2f(UC[(size_t)(m0 + tb + k) * 512 + ch]); gg[k] = bf2f(GT[(size_t)(m0 + tb + k) * 512 + ch]); }
; #pragma unroll
;                     for (int k = 3; k >= 0; --k) { float a, b; scan_coef(pg8::fast_sigmoid(rr[k] + brb), pg8::fast_sigmoid(ii[k] + bib), uu[k], spb, a, b); hb = a * hb + b;
;                         const float y = gelu_tanh(gg[k]) * (hl[(tb + k) * 512 + ch] + hb); YC[(size_t)(m0 + tb + k) * 512 + ch] = (bf16_t)(cvt_pk_bf16(y, y) & 0xffff); } }
	v_rcp_f32_e32 v55, v55
	v_rcp_f32_e32 v58, v58
	v_mul_f32_e32 v48, v43, v48
	v_mul_f32_e32 v51, v43, v51
	v_mul_f32_e32 v54, v43, v54
	v_mul_f32_e32 v57, v43, v57
	v_mul_f32_e32 v49, v49, v50
	v_mul_f32_e32 v52, v52, v53
	v_mul_f32_e32 v55, v55, v56
	v_mul_f32_e32 v58, v58, v59
	v_mul_f32_e32 v48, 0x3fb8aa3b, v48
	v_mul_f32_e32 v51, 0x3fb8aa3b, v51
	v_mul_f32_e32 v54, 0x3fb8aa3b, v54
	v_mul_f32_e32 v57, 0x3fb8aa3b, v57
	v_exp_f32_e32 v48, v48
	v_exp_f32_e32 v51, v51
	v_exp_f32_e32 v54, v54
	v_exp_f32_e32 v57, v57
	v_sub_f32_e32 v50, 1.0, v48
	v_sub_f32_e32 v53, 1.0, v51
	v_sub_f32_e32 v56, 1.0, v54
	v_sub_f32_e32 v59, 1.0, v57
	v_add_f32_e32 v125, 1.0, v48
	v_add_f32_e32 v121, 1.0, v51
	v_add_f32_e32 v117, 1.0, v54
	v_add_f32_e32 v113, 1.0, v57
	v_mul_f32_e32 v50, v50, v125
	v_mul_f32_e32 v53, v53, v121
	v_mul_f32_e32 v56, v56, v117
	v_mul_f32_e32 v59, v59, v113
	v_max_f32_e32 v50, 0, v50
	v_max_f32_e32 v53, 0, v53
	v_max_f32_e32 v56, 0, v56
	v_max_f32_e32 v59, 0, v59
	v_sqrt_f32_e32 v50, v50
	v_sqrt_f32_e32 v53, v53
	v_sqrt_f32_e32 v56, v56
	v_sqrt_f32_e32 v59, v59
	v_mul_f32_e32 v49, v49, v50
	v_mul_f32_e32 v52, v52, v53
	v_mul_f32_e32 v55, v55, v56
	v_mul_f32_e32 v58, v58, v59
	v_lshlrev_b32_e32 v127, 16, v127
	v_lshlrev_b32_e32 v123, 16, v123
	v_lshlrev_b32_e32 v119, 16, v119
	v_lshlrev_b32_e32 v115, 16, v115
	v_mul_f32_e32 v60, 0x3d372713, v127
	v_mul_f32_e32 v61, 0x3d372713, v123
	v_mul_f32_e32 v62, 0x3d372713, v119
	v_mul_f32_e32 v63, 0x3d372713, v115
	v_mul_f32_e32 v60, v60, v127
	v_mul_f32_e32 v61, v61, v123
	v_mul_f32_e32 v62, v62, v119
	v_mul_f32_e32 v63, v63, v115
	v_fma_f32 v60, v60, v127, v127
	v_fma_f32 v61, v61, v123, v123
	v_fma_f32 v62, v62, v119, v119
	v_fma_f32 v63, v63, v115, v115
	v_mul_f32_e32 v60, 0x3f4c422a, v60
	v_mul_f32_e32 v61, 0x3f4c422a, v61
	v_mul_f32_e32 v62, 0x3f4c422a, v62
	v_mul_f32_e32 v63, 0x3f4c422a, v63
	v_add_f32_e32 v60, v60, v60
	v_add_f32_e32 v61, v61, v61
	v_add_f32_e32 v62, v62, v62
	v_add_f32_e32 v63, v63, v63
	v_mul_f32_e32 v60, 0x3fb8aa3b, v60
	v_mul_f32_e32 v61, 0x3fb8aa3b, v61
	v_mul_f32_e32 v62, 0x3fb8aa3b, v62
	v_mul_f32_e32 v63, 0x3fb8aa3b, v63
	v_exp_f32_e32 v60, v60
	v_exp_f32_e32 v61, v61
	v_exp_f32_e32 v62, v62
	v_exp_f32_e32 v63, v63
	v_mul_f32_e32 v127, 0.5, v127
	v_mul_f32_e32 v123, 0.5, v123
	v_mul_f32_e32 v119, 0.5, v119
	v_mul_f32_e32 v115, 0.5, v115
	v_add_f32_e32 v60, 1.0, v60
	v_add_f32_e32 v61, 1.0, v61
	v_add_f32_e32 v62, 1.0, v62
	v_add_f32_e32 v63, 1.0, v63
	v_rcp_f32_e32 v60, v60
	v_rcp_f32_e32 v61, v61
	v_rcp_f32_e32 v62, v62
	v_rcp_f32_e32 v63, v63
	v_nop
	v_nop
	v_nop
	v_nop
	v_fma_f32 v60, v60, -2.0, 1.0
	v_fma_f32 v61, v61, -2.0, 1.0
	v_fma_f32 v62, v62, -2.0, 1.0
	v_fma_f32 v63, v63, -2.0, 1.0
	v_add_f32_e32 v60, 1.0, v60
	v_add_f32_e32 v61, 1.0, v61
	v_add_f32_e32 v62, 1.0, v62
	v_add_f32_e32 v63, 1.0, v63
	v_mul_f32_e32 v60, v127, v60
	v_mul_f32_e32 v61, v123, v61
	v_mul_f32_e32 v62, v119, v62
	v_mul_f32_e32 v63, v115, v63
	v_fma_f32 v32, v32, v48, v49
	v_add_f32_e32 v127, v124, v32
	v_mul_f32_e32 v60, v127, v60
	v_fma_f32 v32, v32, v51, v52
	v_add_f32_e32 v123, v120, v32
	v_mul_f32_e32 v61, v123, v61
	v_fma_f32 v32, v32, v54, v55
	v_add_f32_e32 v119, v116, v32
	v_mul_f32_e32 v62, v119, v62
	v_fma_f32 v32, v32, v57, v58
	v_add_f32_e32 v115, v112, v32
	v_mul_f32_e32 v63, v115, v63
	v_cvt_pk_bf16_f32 v60, v60, v60
	v_cvt_pk_bf16_f32 v61, v61, v61
	v_cvt_pk_bf16_f32 v62, v62, v62
	v_cvt_pk_bf16_f32 v63, v63, v63
	global_store_short v8, v60, s[56:57] offset:3072
	global_store_short v8, v61, s[56:57] offset:2048
	global_store_short v8, v62, s[56:57] offset:1024
	global_store_short v8, v63, s[56:57]
	s_sub_u32 s56, s56, 0x1000
	s_subb_u32 s57, s57, 0
	v_lshlrev_b32_e32 v48, 16, v109
	v_lshlrev_b32_e32 v51, 16, v105
	v_lshlrev_b32_e32 v54, 16, v101
	v_lshlrev_b32_e32 v57, 16, v97
	v_and_b32_e32 v49, 0xffff0000, v109
	v_and_b32_e32 v52, 0xffff0000, v105
	v_and_b32_e32 v55, 0xffff0000, v101
	v_and_b32_e32 v58, 0xffff0000, v97
	v_add_f32_e32 v48, v41, v48
	v_add_f32_e32 v51, v41, v51
	v_add_f32_e32 v54, v41, v54
	v_add_f32_e32 v57, v41, v57
	v_add_f32_e32 v49, v42, v49
	v_add_f32_e32 v52, v42, v52
	v_add_f32_e32 v55, v42, v55
	v_add_f32_e32 v58, v42, v58
	v_mul_f32_e32 v48, 0xbfb8aa3b, v48
	v_mul_f32_e32 v51, 0xbfb8aa3b, v51
	v_mul_f32_e32 v54, 0xbfb8aa3b, v54
	v_mul_f32_e32 v57, 0xbfb8aa3b, v57
	v_mul_f32_e32 v49, 0xbfb8aa3b, v49
	v_mul_f32_e32 v52, 0xbfb8aa3b, v52
	v_mul_f32_e32 v55, 0xbfb8aa3b, v55
	v_mul_f32_e32 v58, 0xbfb8aa3b, v58
	v_exp_f32_e32 v48, v48
	v_exp_f32_e32 v51, v51
	v_exp_f32_e32 v54, v54
	v_exp_f32_e32 v57, v57
	v_exp_f32_e32 v49, v49
	v_exp_f32_e32 v52, v52
	v_exp_f32_e32 v55, v55
	v_exp_f32_e32 v58, v58
	v_lshlrev_b32_e32 v50, 16, v110
	v_lshlrev_b32_e32 v53, 16, v106
	v_lshlrev_b32_e32 v56, 16, v102
	v_lshlrev_b32_e32 v59, 16, v98
	v_add_f32_e32 v48, 1.0, v48
	v_add_f32_e32 v51, 1.0, v51
	v_add_f32_e32 v54, 1.0, v54
	v_add_f32_e32 v57, 1.0, v57
	v_add_f32_e32 v49, 1.0, v49
	v_add_f32_e32 v52, 1.0, v52
	v_add_f32_e32 v55, 1.0, v55
	v_add_f32_e32 v58, 1.0, v58
	v_rcp_f32_e32 v48, v48
	v_rcp_f32_e32 v51, v51
	v_rcp_f32_e32 v54, v54
	v_rcp_f32_e32 v57, v57
	v_rcp_f32_e32 v49, v49
	v_rcp_f32_e32 v52, v52
	v_rcp_f32_e32 v55, v55
	v_rcp_f32_e32 v58, v58
	v_mul_f32_e32 v48, v43, v48
	v_mul_f32_e32 v51, v43, v51
	v_mul_f32_e32 v54, v43, v54
	v_mul_f32_e32 v57, v43, v57
	v_mul_f32_e32 v49, v49, v50
	v_mul_f32_e32 v52, v52, v53
	v_mul_f32_e32 v55, v55, v56
	v_mul_f32_e32 v58, v58, v59
	v_mul_f32_e32 v48, 0x3fb8aa3b, v48
	v_mul_f32_e32 v51, 0x3fb8aa3b, v51
	v_mul_f32_e32 v54, 0x3fb8aa3b, v54
	v_mul_f32_e32 v57, 0x3fb8aa3b, v57
	v_exp_f32_e32 v48, v48
; __device__ __forceinline__ unsigned cvt_pk_bf16(float lo, float hi) { unsigned r; asm volatile("v_cvt_pk_bf16_f32 %0, %1, %2" : "=v"(r) : "v"(lo), "v"(hi)); return r; }
; __device__ __forceinline__ float fast_sigmoid(float x) { return __builtin_amdgcn_rcpf(1.f + __builtin_amdgcn_exp2f(-1.4426950408889634f * x)); }
; __device__ __forceinline__ float bf2f(unsigned short h) { return __uint_as_float(((unsigned)h) << 16); }
; __device__ __forceinline__ float bflo(unsigned w) { return __uint_as_float(w << 16); }
; __device__ __forceinline__ float bfhi(unsigned w) { return __uint_as_float(w & 0xffff0000u); }
; __device__ __forceinline__ float gelu_tanh(float x) { const float y = 0.7978845608028654f * (x + 0.044715f * x * x * x); const float t = 1.f - 2.f * __builtin_amdgcn_rcpf(1.f + __expf(2.f * y)); return 0.5f * x * (1.f + t); }
; __device__ __forceinline__ void scan_coef(float r, float i, float u, float sp8, float& a, float& b) { const float la = -sp8 * r; a = __expf(la); b = __builtin_amdgcn_sqrtf(fmaxf((1.f - a) * (1.f + a), 0.f)) * (i * u); }
; __global__ void __launch_bounds__(512) mega_fwd(Params P) {
;     ...
;                 for (int tb = 28; tb >= 0; tb -= 4) { float rr[4], ii[4], uu[4], gg[4];
; #pragma unroll
;                     for (int k = 0; k < 4; ++k) { const bf16_t* gp = XN + (size_t)(m0 + tb + k) * 2048; { const unsigned g2 = *(const unsigned*)(gp + ch * 4 + 2); rr[k] = bflo(g2); ii[k] = bfhi(g2); }
;                         uu[k] = bf2f(UC[(size_t)(m0 + tb + k) * 512 + ch]); gg[k] = bf2f(GT[(size_t)(m0 + tb + k) * 512 + ch]); }
; #pragma unroll
;                     for (int k = 3; k >= 0; --k) { float a, b; scan_coef(pg8::fast_sigmoid(rr[k] + brb), pg8::fast_sigmoid(ii[k] + bib), uu[k], spb, a, b); hb = a * hb + b;
;                         const float y = gelu_tanh(gg[k]) * (hl[(tb + k) * 512 + ch] + hb); YC[(size_t)(m0 + tb + k) * 512 + ch] = (bf16_t)(cvt_pk_bf16(y, y) & 0xffff); } }
	v_exp_f32_e32 v51, v51
	v_exp_f32_e32 v54, v54
	v_exp_f32_e32 v57, v57
	v_sub_f32_e32 v50, 1.0, v48
	v_sub_f32_e32 v53, 1.0, v51
	v_sub_f32_e32 v56, 1.0, v54
	v_sub_f32_e32 v59, 1.0, v57
	v_add_f32_e32 v109, 1.0, v48
	v_add_f32_e32 v105, 1.0, v51
	v_add_f32_e32 v101, 1.0, v54
	v_add_f32_e32 v97, 1.0, v57
	v_mul_f32_e32 v50, v50, v109
	v_mul_f32_e32 v53, v53, v105
	v_mul_f32_e32 v56, v56, v101
	v_mul_f32_e32 v59, v59, v97
	v_max_f32_e32 v50, 0, v50
	v_max_f32_e32 v53, 0, v53
	v_max_f32_e32 v56, 0, v56
	v_max_f32_e32 v59, 0, v59
	v_sqrt_f32_e32 v50, v50
	v_sqrt_f32_e32 v53, v53
	v_sqrt_f32_e32 v56, v56
	v_sqrt_f32_e32 v59, v59
	v_mul_f32_e32 v49, v49, v50
	v_mul_f32_e32 v52, v52, v53
	v_mul_f32_e32 v55, v55, v56
	v_mul_f32_e32 v58, v58, v59
	v_lshlrev_b32_e32 v111, 16, v111
	v_lshlrev_b32_e32 v107, 16, v107
	v_lshlrev_b32_e32 v103, 16, v103
	v_lshlrev_b32_e32 v99, 16, v99
	v_mul_f32_e32 v60, 0x3d372713, v111
	v_mul_f32_e32 v61, 0x3d372713, v107
	v_mul_f32_e32 v62, 0x3d372713, v103
	v_mul_f32_e32 v63, 0x3d372713, v99
	v_mul_f32_e32 v60, v60, v111
	v_mul_f32_e32 v61, v61, v107
	v_mul_f32_e32 v62, v62, v103
	v_mul_f32_e32 v63, v63, v99
	v_fma_f32 v60, v60, v111, v111
	v_fma_f32 v61, v61, v107, v107
	v_fma_f32 v62, v62, v103, v103
	v_fma_f32 v63, v63, v99, v99
	v_mul_f32_e32 v60, 0x3f4c422a, v60
	v_mul_f32_e32 v61, 0x3f4c422a, v61
	v_mul_f32_e32 v62, 0x3f4c422a, v62
	v_mul_f32_e32 v63, 0x3f4c422a, v63
	v_add_f32_e32 v60, v60, v60
	v_add_f32_e32 v61, v61, v61
	v_add_f32_e32 v62, v62, v62
	v_add_f32_e32 v63, v63, v63
	v_mul_f32_e32 v60, 0x3fb8aa3b, v60
	v_mul_f32_e32 v61, 0x3fb8aa3b, v61
	v_mul_f32_e32 v62, 0x3fb8aa3b, v62
	v_mul_f32_e32 v63, 0x3fb8aa3b, v63
	v_exp_f32_e32 v60, v60
	v_exp_f32_e32 v61, v61
	v_exp_f32_e32 v62, v62
	v_exp_f32_e32 v63, v63
	v_mul_f32_e32 v111, 0.5, v111
	v_mul_f32_e32 v107, 0.5, v107
	v_mul_f32_e32 v103, 0.5, v103
	v_mul_f32_e32 v99, 0.5, v99
	v_add_f32_e32 v60, 1.0, v60
	v_add_f32_e32 v61, 1.0, v61
	v_add_f32_e32 v62, 1.0, v62
	v_add_f32_e32 v63, 1.0, v63
	v_rcp_f32_e32 v60, v60
	v_rcp_f32_e32 v61, v61
	v_rcp_f32_e32 v62, v62
	v_rcp_f32_e32 v63, v63
	v_nop
	v_nop
	v_nop
	v_nop
	v_fma_f32 v60, v60, -2.0, 1.0
	v_fma_f32 v61, v61, -2.0, 1.0
	v_fma_f32 v62, v62, -2.0, 1.0
	v_fma_f32 v63, v63, -2.0, 1.0
	v_add_f32_e32 v60, 1.0, v60
	v_add_f32_e32 v61, 1.0, v61
	v_add_f32_e32 v62, 1.0, v62
	v_add_f32_e32 v63, 1.0, v63
	v_mul_f32_e32 v60, v111, v60
	v_mul_f32_e32 v61, v107, v61
	v_mul_f32_e32 v62, v103, v62
	v_mul_f32_e32 v63, v99, v63
	v_fma_f32 v32, v32, v48, v49
	v_add_f32_e32 v111, v108, v32
	v_mul_f32_e32 v60, v111, v60
	v_fma_f32 v32, v32, v51, v52
	v_add_f32_e32 v107, v104, v32
	v_mul_f32_e32 v61, v107, v61
	v_fma_f32 v32, v32, v54, v55
	v_add_f32_e32 v103, v100, v32
	v_mul_f32_e32 v62, v103, v62
	v_fma_f32 v32, v32, v57, v58
	v_add_f32_e32 v99, v96, v32
	v_mul_f32_e32 v63, v99, v63
	v_cvt_pk_bf16_f32 v60, v60, v60
	v_cvt_pk_bf16_f32 v61, v61, v61
	v_cvt_pk_bf16_f32 v62, v62, v62
	v_cvt_pk_bf16_f32 v63, v63, v63
	global_store_short v8, v60, s[56:57] offset:3072
	global_store_short v8, v61, s[56:57] offset:2048
	global_store_short v8, v62, s[56:57] offset:1024
	global_store_short v8, v63, s[56:57]
	s_sub_u32 s56, s56, 0x1000
	s_subb_u32 s57, s57, 0
	v_lshlrev_b32_e32 v48, 16, v93
	v_lshlrev_b32_e32 v51, 16, v89
	v_lshlrev_b32_e32 v54, 16, v85
	v_lshlrev_b32_e32 v57, 16, v81
	v_and_b32_e32 v49, 0xffff0000, v93
	v_and_b32_e32 v52, 0xffff0000, v89
	v_and_b32_e32 v55, 0xffff0000, v85
	v_and_b32_e32 v58, 0xffff0000, v81
	v_add_f32_e32 v48, v41, v48
	v_add_f32_e32 v51, v41, v51
	v_add_f32_e32 v54, v41, v54
	v_add_f32_e32 v57, v41, v57
	v_add_f32_e32 v49, v42, v49
	v_add_f32_e32 v52, v42, v52
	v_add_f32_e32 v55, v42, v55
	v_add_f32_e32 v58, v42, v58
	v_mul_f32_e32 v48, 0xbfb8aa3b, v48
	v_mul_f32_e32 v51, 0xbfb8aa3b, v51
	v_mul_f32_e32 v54, 0xbfb8aa3b, v54
	v_mul_f32_e32 v57, 0xbfb8aa3b, v57
	v_mul_f32_e32 v49, 0xbfb8aa3b, v49
	v_mul_f32_e32 v52, 0xbfb8aa3b, v52
	v_mul_f32_e32 v55, 0xbfb8aa3b, v55
	v_mul_f32_e32 v58, 0xbfb8aa3b, v58
	v_exp_f32_e32 v48, v48
	v_exp_f32_e32 v51, v51
	v_exp_f32_e32 v54, v54
	v_exp_f32_e32 v57, v57
	v_exp_f32_e32 v49, v49
	v_exp_f32_e32 v52, v52
	v_exp_f32_e32 v55, v55
	v_exp_f32_e32 v58, v58
	v_lshlrev_b32_e32 v50, 16, v94
	v_lshlrev_b32_e32 v53, 16, v90
	v_lshlrev_b32_e32 v56, 16, v86
	v_lshlrev_b32_e32 v59, 16, v82
	v_add_f32_e32 v48, 1.0, v48
	v_add_f32_e32 v51, 1.0, v51
	v_add_f32_e32 v54, 1.0, v54
	v_add_f32_e32 v57, 1.0, v57
	v_add_f32_e32 v49, 1.0, v49
	v_add_f32_e32 v52, 1.0, v52
	v_add_f32_e32 v55, 1.0, v55
	v_add_f32_e32 v58, 1.0, v58
	v_rcp_f32_e32 v48, v48
	v_rcp_f32_e32 v51, v51
	v_rcp_f32_e32 v54, v54
	v_rcp_f32_e32 v57, v57
	v_rcp_f32_e32 v49, v49
	v_rcp_f32_e32 v52, v52
	v_rcp_f32_e32 v55, v55
	v_rcp_f32_e32 v58, v58
	v_mul_f32_e32 v48, v43, v48
	v_mul_f32_e32 v51, v43, v51
	v_mul_f32_e32 v54, v43, v54
	v_mul_f32_e32 v57, v43, v57
	v_mul_f32_e32 v49, v49, v50
	v_mul_f32_e32 v52, v52, v53
	v_mul_f32_e32 v55, v55, v56
	v_mul_f32_e32 v58, v58, v59
	v_mul_f32_e32 v48, 0x3fb8aa3b, v48
	v_mul_f32_e32 v51, 0x3fb8aa3b, v51
	v_mul_f32_e32 v54, 0x3fb8aa3b, v54
	v_mul_f32_e32 v57, 0x3fb8aa3b, v57
	v_exp_f32_e32 v48, v48
	v_exp_f32_e32 v51, v51
	v_exp_f32_e32 v54, v54
	v_exp_f32_e32 v57, v57
	v_sub_f32_e32 v50, 1.0, v48
	v_sub_f32_e32 v53, 1.0, v51
	v_sub_f32_e32 v56, 1.0, v54
	v_sub_f32_e32 v59, 1.0, v57
	v_add_f32_e32 v93, 1.0, v48
	v_add_f32_e32 v89, 1.0, v51
	v_add_f32_e32 v85, 1.0, v54
	v_add_f32_e32 v81, 1.0, v57
	v_mul_f32_e32 v50, v50, v93
	v_mul_f32_e32 v53, v53, v89
	v_mul_f32_e32 v56, v56, v85
	v_mul_f32_e32 v59, v59, v81
	v_max_f32_e32 v50, 0, v50
	v_max_f32_e32 v53, 0, v53
; __device__ __forceinline__ unsigned cvt_pk_bf16(float lo, float hi) { unsigned r; asm volatile("v_cvt_pk_bf16_f32 %0, %1, %2" : "=v"(r) : "v"(lo), "v"(hi)); return r; }
; __device__ __forceinline__ float fast_sigmoid(float x) { return __builtin_amdgcn_rcpf(1.f + __builtin_amdgcn_exp2f(-1.4426950408889634f * x)); }
; __device__ __forceinline__ float bf2f(unsigned short h) { return __uint_as_float(((unsigned)h) << 16); }
; __device__ __forceinline__ float bflo(unsigned w) { return __uint_as_float(w << 16); }
; __device__ __forceinline__ float bfhi(unsigned w) { return __uint_as_float(w & 0xffff0000u); }
; __device__ __forceinline__ float gelu_tanh(float x) { const float y = 0.7978845608028654f * (x + 0.044715f * x * x * x); const float t = 1.f - 2.f * __builtin_amdgcn_rcpf(1.f + __expf(2.f * y)); return 0.5f * x * (1.f + t); }
; __device__ __forceinline__ void scan_coef(float r, float i, float u, float sp8, float& a, float& b) { const float la = -sp8 * r; a = __expf(la); b = __builtin_amdgcn_sqrtf(fmaxf((1.f - a) * (1.f + a), 0.f)) * (i * u); }
; __global__ void __launch_bounds__(512) mega_fwd(Params P) {
;     ...
;                 for (int tb = 28; tb >= 0; tb -= 4) { float rr[4], ii[4], uu[4], gg[4];
; #pragma unroll
;                     for (int k = 0; k < 4; ++k) { const bf16_t* gp = XN + (size_t)(m0 + tb + k) * 2048; { const unsigned g2 = *(const unsigned*)(gp + ch * 4 + 2); rr[k] = bflo(g2); ii[k] = bfhi(g2); }
;                         uu[k] = bf2f(UC[(size_t)(m0 + tb + k) * 512 + ch]); gg[k] = bf2f(GT[(size_t)(m0 + tb + k) * 512 + ch]); }
; #pragma unroll
;                     for (int k = 3; k >= 0; --k) { float a, b; scan_coef(pg8::fast_sigmoid(rr[k] + brb), pg8::fast_sigmoid(ii[k] + bib), uu[k], spb, a, b); hb = a * hb + b;
;                         const float y = gelu_tanh(gg[k]) * (hl[(tb + k) * 512 + ch] + hb); YC[(size_t)(m0 + tb + k) * 512 + ch] = (bf16_t)(cvt_pk_bf16(y, y) & 0xffff); } }
	v_max_f32_e32 v56, 0, v56
	v_max_f32_e32 v59, 0, v59
	v_sqrt_f32_e32 v50, v50
	v_sqrt_f32_e32 v53, v53
	v_sqrt_f32_e32 v56, v56
	v_sqrt_f32_e32 v59, v59
	v_mul_f32_e32 v49, v49, v50
	v_mul_f32_e32 v52, v52, v53
	v_mul_f32_e32 v55, v55, v56
	v_mul_f32_e32 v58, v58, v59
	v_lshlrev_b32_e32 v95, 16, v95
	v_lshlrev_b32_e32 v91, 16, v91
	v_lshlrev_b32_e32 v87, 16, v87
	v_lshlrev_b32_e32 v83, 16, v83
	v_mul_f32_e32 v60, 0x3d372713, v95
	v_mul_f32_e32 v61, 0x3d372713, v91
	v_mul_f32_e32 v62, 0x3d372713, v87
	v_mul_f32_e32 v63, 0x3d372713, v83
	v_mul_f32_e32 v60, v60, v95
	v_mul_f32_e32 v61, v61, v91
	v_mul_f32_e32 v62, v62, v87
	v_mul_f32_e32 v63, v63, v83
	v_fma_f32 v60, v60, v95, v95
	v_fma_f32 v61, v61, v91, v91
	v_fma_f32 v62, v62, v87, v87
	v_fma_f32 v63, v63, v83, v83
	v_mul_f32_e32 v60, 0x3f4c422a, v60
	v_mul_f32_e32 v61, 0x3f4c422a, v61
	v_mul_f32_e32 v62, 0x3f4c422a, v62
	v_mul_f32_e32 v63, 0x3f4c422a, v63
	v_add_f32_e32 v60, v60, v60
	v_add_f32_e32 v61, v61, v61
	v_add_f32_e32 v62, v62, v62
	v_add_f32_e32 v63, v63, v63
	v_mul_f32_e32 v60, 0x3fb8aa3b, v60
	v_mul_f32_e32 v61, 0x3fb8aa3b, v61
	v_mul_f32_e32 v62, 0x3fb8aa3b, v62
	v_mul_f32_e32 v63, 0x3fb8aa3b, v63
	v_exp_f32_e32 v60, v60
	v_exp_f32_e32 v61, v61
	v_exp_f32_e32 v62, v62
	v_exp_f32_e32 v63, v63
	v_mul_f32_e32 v95, 0.5, v95
	v_mul_f32_e32 v91, 0.5, v91
	v_mul_f32_e32 v87, 0.5, v87
	v_mul_f32_e32 v83, 0.5, v83
	v_add_f32_e32 v60, 1.0, v60
	v_add_f32_e32 v61, 1.0, v61
	v_add_f32_e32 v62, 1.0, v62
	v_add_f32_e32 v63, 1.0, v63
	v_rcp_f32_e32 v60, v60
	v_rcp_f32_e32 v61, v61
	v_rcp_f32_e32 v62, v62
	v_rcp_f32_e32 v63, v63
	v_nop
	v_nop
	v_nop
	v_nop
	v_fma_f32 v60, v60, -2.0, 1.0
	v_fma_f32 v61, v61, -2.0, 1.0
	v_fma_f32 v62, v62, -2.0, 1.0
	v_fma_f32 v63, v63, -2.0, 1.0
	v_add_f32_e32 v60, 1.0, v60
	v_add_f32_e32 v61, 1.0, v61
	v_add_f32_e32 v62, 1.0, v62
	v_add_f32_e32 v63, 1.0, v63
	v_mul_f32_e32 v60, v95, v60
	v_mul_f32_e32 v61, v91, v61
	v_mul_f32_e32 v62, v87, v62
	v_mul_f32_e32 v63, v83, v63
	v_fma_f32 v32, v32, v48, v49
	v_add_f32_e32 v95, v92, v32
	v_mul_f32_e32 v60, v95, v60
	v_fma_f32 v32, v32, v51, v52
	v_add_f32_e32 v91, v88, v32
	v_mul_f32_e32 v61, v91, v61
	v_fma_f32 v32, v32, v54, v55
	v_add_f32_e32 v87, v84, v32
	v_mul_f32_e32 v62, v87, v62
	v_fma_f32 v32, v32, v57, v58
	v_add_f32_e32 v83, v80, v32
	v_mul_f32_e32 v63, v83, v63
	v_cvt_pk_bf16_f32 v60, v60, v60
	v_cvt_pk_bf16_f32 v61, v61, v61
	v_cvt_pk_bf16_f32 v62, v62, v62
	v_cvt_pk_bf16_f32 v63, v63, v63
	global_store_short v8, v60, s[56:57] offset:3072
	global_store_short v8, v61, s[56:57] offset:2048
	global_store_short v8, v62, s[56:57] offset:1024
	global_store_short v8, v63, s[56:57]
	s_sub_u32 s56, s56, 0x1000
	s_subb_u32 s57, s57, 0
	v_lshlrev_b32_e32 v48, 16, v77
	v_lshlrev_b32_e32 v51, 16, v73
	v_lshlrev_b32_e32 v54, 16, v69
	v_lshlrev_b32_e32 v57, 16, v65
	v_and_b32_e32 v49, 0xffff0000, v77
	v_and_b32_e32 v52, 0xffff0000, v73
	v_and_b32_e32 v55, 0xffff0000, v69
	v_and_b32_e32 v58, 0xffff0000, v65
	v_add_f32_e32 v48, v41, v48
	v_add_f32_e32 v51, v41, v51
	v_add_f32_e32 v54, v41, v54
	v_add_f32_e32 v57, v41, v57
	v_add_f32_e32 v49, v42, v49
	v_add_f32_e32 v52, v42, v52
	v_add_f32_e32 v55, v42, v55
	v_add_f32_e32 v58, v42, v58
	v_mul_f32_e32 v48, 0xbfb8aa3b, v48
	v_mul_f32_e32 v51, 0xbfb8aa3b, v51
	v_mul_f32_e32 v54, 0xbfb8aa3b, v54
	v_mul_f32_e32 v57, 0xbfb8aa3b, v57
	v_mul_f32_e32 v49, 0xbfb8aa3b, v49
	v_mul_f32_e32 v52, 0xbfb8aa3b, v52
	v_mul_f32_e32 v55, 0xbfb8aa3b, v55
	v_mul_f32_e32 v58, 0xbfb8aa3b, v58
	v_exp_f32_e32 v48, v48
	v_exp_f32_e32 v51, v51
	v_exp_f32_e32 v54, v54
	v_exp_f32_e32 v57, v57
	v_exp_f32_e32 v49, v49
	v_exp_f32_e32 v52, v52
	v_exp_f32_e32 v55, v55
	v_exp_f32_e32 v58, v58
	v_lshlrev_b32_e32 v50, 16, v78
	v_lshlrev_b32_e32 v53, 16, v74
	v_lshlrev_b32_e32 v56, 16, v70
	v_lshlrev_b32_e32 v59, 16, v66
	v_add_f32_e32 v48, 1.0, v48
	v_add_f32_e32 v51, 1.0, v51
	v_add_f32_e32 v54, 1.0, v54
	v_add_f32_e32 v57, 1.0, v57
	v_add_f32_e32 v49, 1.0, v49
	v_add_f32_e32 v52, 1.0, v52
; __device__ __forceinline__ unsigned cvt_pk_bf16(float lo, float hi) { unsigned r; asm volatile("v_cvt_pk_bf16_f32 %0, %1, %2" : "=v"(r) : "v"(lo), "v"(hi)); return r; }
; __device__ __forceinline__ float fast_sigmoid(float x) { return __builtin_amdgcn_rcpf(1.f + __builtin_amdgcn_exp2f(-1.4426950408889634f * x)); }
; __device__ __forceinline__ float bf2f(unsigned short h) { return __uint_as_float(((unsigned)h) << 16); }
; __device__ __forceinline__ float bflo(unsigned w) { return __uint_as_float(w << 16); }
; __device__ __forceinline__ float bfhi(unsigned w) { return __uint_as_float(w & 0xffff0000u); }
; __device__ __forceinline__ float gelu_tanh(float x) { const float y = 0.7978845608028654f * (x + 0.044715f * x * x * x); const float t = 1.f - 2.f * __builtin_amdgcn_rcpf(1.f + __expf(2.f * y)); return 0.5f * x * (1.f + t); }
; __device__ __forceinline__ void scan_coef(float r, float i, float u, float sp8, float& a, float& b) { const float la = -sp8 * r; a = __expf(la); b = __builtin_amdgcn_sqrtf(fmaxf((1.f - a) * (1.f + a), 0.f)) * (i * u); }
; __global__ void __launch_bounds__(512) mega_fwd(Params P) {
;     ...
;                 for (int tb = 28; tb >= 0; tb -= 4) { float rr[4], ii[4], uu[4], gg[4];
; #pragma unroll
;                     for (int k = 0; k < 4; ++k) { const bf16_t* gp = XN + (size_t)(m0 + tb + k) * 2048; { const unsigned g2 = *(const unsigned*)(gp + ch * 4 + 2); rr[k] = bflo(g2); ii[k] = bfhi(g2); }
;                         uu[k] = bf2f(UC[(size_t)(m0 + tb + k) * 512 + ch]); gg[k] = bf2f(GT[(size_t)(m0 + tb + k) * 512 + ch]); }
; #pragma unroll
;                     for (int k = 3; k >= 0; --k) { float a, b; scan_coef(pg8::fast_sigmoid(rr[k] + brb), pg8::fast_sigmoid(ii[k] + bib), uu[k], spb, a, b); hb = a * hb + b;
;                         const float y = gelu_tanh(gg[k]) * (hl[(tb + k) * 512 + ch] + hb); YC[(size_t)(m0 + tb + k) * 512 + ch] = (bf16_t)(cvt_pk_bf16(y, y) & 0xffff); } }
	v_add_f32_e32 v55, 1.0, v55
	v_add_f32_e32 v58, 1.0, v58
	v_rcp_f32_e32 v48, v48
	v_rcp_f32_e32 v51, v51
	v_rcp_f32_e32 v54, v54
	v_rcp_f32_e32 v57, v57
	v_rcp_f32_e32 v49, v49
	v_rcp_f32_e32 v52, v52
	v_rcp_f32_e32 v55, v55
	v_rcp_f32_e32 v58, v58
	v_mul_f32_e32 v48, v43, v48
	v_mul_f32_e32 v51, v43, v51
	v_mul_f32_e32 v54, v43, v54
	v_mul_f32_e32 v57, v43, v57
	v_mul_f32_e32 v49, v49, v50
	v_mul_f32_e32 v52, v52, v53
	v_mul_f32_e32 v55, v55, v56
	v_mul_f32_e32 v58, v58, v59
	v_mul_f32_e32 v48, 0x3fb8aa3b, v48
	v_mul_f32_e32 v51, 0x3fb8aa3b, v51
	v_mul_f32_e32 v54, 0x3fb8aa3b, v54
	v_mul_f32_e32 v57, 0x3fb8aa3b, v57
	v_exp_f32_e32 v48, v48
	v_exp_f32_e32 v51, v51
	v_exp_f32_e32 v54, v54
	v_exp_f32_e32 v57, v57
	v_sub_f32_e32 v50, 1.0, v48
	v_sub_f32_e32 v53, 1.0, v51
	v_sub_f32_e32 v56, 1.0, v54
	v_sub_f32_e32 v59, 1.0, v57
	v_add_f32_e32 v77, 1.0, v48
	v_add_f32_e32 v73, 1.0, v51
	v_add_f32_e32 v69, 1.0, v54
	v_add_f32_e32 v65, 1.0, v57
	v_mul_f32_e32 v50, v50, v77
	v_mul_f32_e32 v53, v53, v73
	v_mul_f32_e32 v56, v56, v69
	v_mul_f32_e32 v59, v59, v65
	v_max_f32_e32 v50, 0, v50
	v_max_f32_e32 v53, 0, v53
	v_max_f32_e32 v56, 0, v56
	v_max_f32_e32 v59, 0, v59
	v_sqrt_f32_e32 v50, v50
	v_sqrt_f32_e32 v53, v53
	v_sqrt_f32_e32 v56, v56
	v_sqrt_f32_e32 v59, v59
	v_mul_f32_e32 v49, v49, v50
	v_mul_f32_e32 v52, v52, v53
	v_mul_f32_e32 v55, v55, v56
	v_mul_f32_e32 v58, v58, v59
	v_lshlrev_b32_e32 v79, 16, v79
	v_lshlrev_b32_e32 v75, 16, v75
	v_lshlrev_b32_e32 v71, 16, v71
	v_lshlrev_b32_e32 v67, 16, v67
	v_mul_f32_e32 v60, 0x3d372713, v79
	v_mul_f32_e32 v61, 0x3d372713, v75
	v_mul_f32_e32 v62, 0x3d372713, v71
	v_mul_f32_e32 v63, 0x3d372713, v67
	v_mul_f32_e32 v60, v60, v79
	v_mul_f32_e32 v61, v61, v75
	v_mul_f32_e32 v62, v62, v71
	v_mul_f32_e32 v63, v63, v67
	v_fma_f32 v60, v60, v79, v79
	v_fma_f32 v61, v61, v75, v75
	v_fma_f32 v62, v62, v71, v71
	v_fma_f32 v63, v63, v67, v67
	v_mul_f32_e32 v60, 0x3f4c422a, v60
	v_mul_f32_e32 v61, 0x3f4c422a, v61
	v_mul_f32_e32 v62, 0x3f4c422a, v62
	v_mul_f32_e32 v63, 0x3f4c422a, v63
	v_add_f32_e32 v60, v60, v60
	v_add_f32_e32 v61, v61, v61
	v_add_f32_e32 v62, v62, v62
	v_add_f32_e32 v63, v63, v63
	v_mul_f32_e32 v60, 0x3fb8aa3b, v60
	v_mul_f32_e32 v61, 0x3fb8aa3b, v61
	v_mul_f32_e32 v62, 0x3fb8aa3b, v62
	v_mul_f32_e32 v63, 0x3fb8aa3b, v63
	v_exp_f32_e32 v60, v60
	v_exp_f32_e32 v61, v61
	v_exp_f32_e32 v62, v62
	v_exp_f32_e32 v63, v63
	v_mul_f32_e32 v79, 0.5, v79
	v_mul_f32_e32 v75, 0.5, v75
	v_mul_f32_e32 v71, 0.5, v71
	v_mul_f32_e32 v67, 0.5, v67
	v_add_f32_e32 v60, 1.0, v60
	v_add_f32_e32 v61, 1.0, v61
	v_add_f32_e32 v62, 1.0, v62
	v_add_f32_e32 v63, 1.0, v63
	v_rcp_f32_e32 v60, v60
	v_rcp_f32_e32 v61, v61
	v_rcp_f32_e32 v62, v62
	v_rcp_f32_e32 v63, v63
	v_nop
	v_nop
	v_nop
	v_nop
	v_fma_f32 v60, v60, -2.0, 1.0
	v_fma_f32 v61, v61, -2.0, 1.0
	v_fma_f32 v62, v62, -2.0, 1.0
	v_fma_f32 v63, v63, -2.0, 1.0
	v_add_f32_e32 v60, 1.0, v60
	v_add_f32_e32 v61, 1.0, v61
	v_add_f32_e32 v62, 1.0, v62
	v_add_f32_e32 v63, 1.0, v63
	v_mul_f32_e32 v60, v79, v60
	v_mul_f32_e32 v61, v75, v61
	v_mul_f32_e32 v62, v71, v62
	v_mul_f32_e32 v63, v67, v63
	v_fma_f32 v32, v32, v48, v49
	v_add_f32_e32 v79, v76, v32
	v_mul_f32_e32 v60, v79, v60
	v_fma_f32 v32, v32, v51, v52
	v_add_f32_e32 v75, v72, v32
	v_mul_f32_e32 v61, v75, v61
	v_fma_f32 v32, v32, v54, v55
	v_add_f32_e32 v71, v68, v32
	v_mul_f32_e32 v62, v71, v62
	v_fma_f32 v32, v32, v57, v58
	v_add_f32_e32 v67, v64, v32
	v_mul_f32_e32 v63, v67, v63
	v_cvt_pk_bf16_f32 v60, v60, v60
	v_cvt_pk_bf16_f32 v61, v61, v61
	v_cvt_pk_bf16_f32 v62, v62, v62
	v_cvt_pk_bf16_f32 v63, v63, v63
	global_store_short v8, v60, s[56:57] offset:3072
	global_store_short v8, v61, s[56:57] offset:2048
	global_store_short v8, v62, s[56:57] offset:1024
	global_store_short v8, v63, s[56:57]
	v_readlane_b32 s38, v254, 62
	s_add_i32 s54, s54, s3
	s_add_i32 s29, s29, s38
	s_add_i32 s52, s52, s38
	s_add_i32 s50, s50, s38
	s_add_i32 s48, s48, s38
	s_add_i32 s46, s46, s38
	s_cmpk_gt_i32 s54, 0x4ff
	s_cbranch_scc0 .LBB0_1327
